# P4 dilation-16 attention groups: K/V fragment loads batched ahead of their MFMAs (were issued one by one behind vmcnt(0))
# speedup vs baseline: 1.0220x; 1.0037x over previous
; __device__ __forceinline__ f32x4 mfma16(bf16x8 a, bf16x8 b, f32x4 c) { return __builtin_amdgcn_mfma_f32_16x16x32_bf16(a, b, c, 0, 0, 0); }
; template <int BR>
; __device__ __forceinline__ void pattn_group(const bf16* P1, const bf16* VTB, LAS float* O, LAS float* Mx, LAS float* Ls, int t0, int h, int gi, int i16, int g) {
;     ...
;     if (BR == 0) { r = 0; ql0 = 16 * gi; mq0 = t0 + 16 * gi; }
;     else if (BR == 1) { r = gi & 3; ql0 = 64 * (gi >> 2) + r; mq0 = (t0 >> 2) + 16 * (gi >> 2); }
;     else { r = gi; ql0 = r; mq0 = t0 >> 4; }
;     const bf16* qrow = P1 + (size_t)((mq0 + i16) * dil + r) * P1W + C_AQ + h * 64 + 8 * g;
;     const bf16x8 qf0 = ldfrag(qrow), qf1 = ldfrag(qrow + 32);
;     f32x4 s[5][2];
; #pragma unroll
;     for (int kb = 0; kb < 5; ++kb)
; #pragma unroll
;         for (int hf = 0; hf < 2; ++hf) {
;             int mk = mq0 - 144 + 32 * kb + 8 * (i16 >> 2) + (i16 & 3) + 4 * hf; mk = mk < 0 ? 0 : mk;
;             const bf16* krow = P1 + (size_t)(mk * dil + r) * P1W + C_AK + h * 64 + 8 * g;
;             f32x4 acc = {0.f, 0.f, 0.f, 0.f};
;             acc = mfma16(ldfrag(krow), qf0, acc); acc = mfma16(ldfrag(krow + 32), qf1, acc);
;             s[kb][hf] = acc;
;         }
;     float mx = -1e30f;
; #pragma unroll
;     for (int kb = 0; kb < 5; ++kb)
; #pragma unroll
;         for (int hf = 0; hf < 2; ++hf)
; #pragma unroll
;             for (int e = 0; e < 4; ++e) {
;                 const int c = -144 + 32 * kb + 8 * g + 4 * hf + e, dist = i16 - c;
;                 const bool ok = dist >= 0 && dist <= 128 && (mq0 + c) >= 0;
;                 const float v = ok ? s[kb][hf][e] : -1e30f; s[kb][hf][e] = v; mx = fmaxf(mx, v);
.LBB0_982:
	s_or_b64 exec, exec, s[0:1]
	s_lshl_b32 s34, s18, 4
	s_not_b32 s56, s34
	v_readlane_b32 s0, v254, 15
	v_cmp_lt_u32_e32 vcc, s56, v164
	v_readlane_b32 s1, v254, 16
	s_and_b64 s[76:77], s[0:1], vcc
	v_readlane_b32 s0, v254, 46
	v_cmp_lt_u32_e32 vcc, s56, v165
	v_readlane_b32 s1, v254, 47
	v_readlane_b32 s2, v254, 25
	s_and_b64 s[92:93], s[0:1], vcc
	v_cmp_lt_u32_e64 s[0:1], s56, v167
	v_readlane_b32 s3, v254, 26
	s_and_b64 s[84:85], s[2:3], s[0:1]
	v_readlane_b32 s2, v254, 21
	v_cmp_lt_u32_e64 s[0:1], s56, v169
	v_readlane_b32 s3, v254, 22
	s_and_b64 s[16:17], s[2:3], s[0:1]
	v_readlane_b32 s2, v253, 55
	v_cmp_lt_u32_e64 s[0:1], s56, v170
	v_readlane_b32 s3, v253, 56
	s_and_b64 s[14:15], s[2:3], s[0:1]
	v_readlane_b32 s2, v254, 9
	v_or_b32_e32 v2, s34, v1
	s_add_i32 s35, s34, 0xffffff70
	v_cmp_lt_u32_e64 s[0:1], s56, v171
	v_readlane_b32 s3, v254, 10
	v_readlane_b32 s4, v254, 23
	v_lshlrev_b32_e32 v67, 4, v2
	v_or_b32_e32 v2, s35, v121
	s_and_b64 s[12:13], s[2:3], s[0:1]
	v_cmp_lt_u32_e64 s[2:3], s56, v172
	v_readlane_b32 s5, v254, 24
	v_add_u32_e32 v2, v2, v115
	s_and_b64 s[30:31], s[4:5], s[2:3]
	v_readlane_b32 s4, v254, 33
	v_cmp_gt_u32_e64 s[36:37], s34, v196
	v_max_i32_e32 v3, 0, v2
	v_readlane_b32 s5, v254, 34
	v_writelane_b32 v254, s36, 52
	v_readlane_b32 s40, v253, 50
	v_lshlrev_b32_e32 v66, 4, v3
	v_max_i32_e32 v3, -4, v2
	v_writelane_b32 v254, s37, 53
	v_cmp_lt_i32_e64 s[36:37], s56, v197
	v_readlane_b32 s41, v253, 51
	v_lshl_add_u32 v65, v3, 4, 64
	v_max_i32_e32 v3, 0xffffffe0, v2
	s_and_b64 s[60:61], s[40:41], s[36:37]
	v_readlane_b32 s40, v254, 62
	v_lshl_add_u32 v64, v3, 4, v229
	v_max_i32_e32 v3, 0xffffffdc, v2
	v_cmp_lt_i32_e64 s[36:37], s56, v198
	v_readlane_b32 s41, v254, 63
	v_lshl_add_u32 v63, v3, 4, v230
	v_max_i32_e32 v3, 0xffffffc0, v2
	s_and_b64 s[44:45], s[40:41], s[36:37]
	v_readlane_b32 s40, v255, 0
	v_lshl_add_u32 v62, v3, 4, v231
	v_max_i32_e32 v3, 0xffffffbc, v2
	v_cmp_lt_i32_e64 s[36:37], s56, v199
	v_readlane_b32 s41, v255, 1
	v_readlane_b32 s42, v255, 2
	v_lshl_add_u32 v61, v3, 4, v232
	v_max_i32_e32 v3, 0xffffffa0, v2
	s_and_b64 s[36:37], s[40:41], s[36:37]
	v_cmp_lt_i32_e64 s[40:41], s56, v200
	v_readlane_b32 s43, v255, 3
	v_readlane_b32 s48, v255, 4
	v_lshl_add_u32 v60, v3, 4, v233
	v_max_i32_e32 v3, 0xffffff9c, v2
	s_and_b64 s[40:41], s[42:43], s[40:41]
	v_cmp_lt_i32_e64 s[42:43], s56, v201
	v_readlane_b32 s49, v255, 5
	v_readlane_b32 s50, v255, 6
	v_lshl_add_u32 v59, v3, 4, v234
	v_max_i32_e32 v3, 0xffffff80, v2
	v_max_i32_e32 v2, 0xffffff7c, v2
	s_and_b64 s[42:43], s[48:49], s[42:43]
	v_cmp_lt_i32_e64 s[48:49], s56, v202
	v_readlane_b32 s51, v255, 7
	v_readlane_b32 vcc_lo, v255, 8
	v_lshl_add_u32 v57, v2, 4, v236
	v_cmp_lt_u32_e64 s[2:3], s56, v173
	v_sub_u32_e32 v2, 0x6f, v114
	s_and_b64 s[48:49], s[50:51], s[48:49]
	v_cmp_lt_i32_e64 s[50:51], s56, v203
	v_readlane_b32 vcc_hi, v255, 9
	s_and_b64 s[10:11], s[4:5], s[2:3]
	v_cmp_gt_u32_e64 s[96:97], s34, v2
	v_cmp_gt_u32_e64 s[2:3], s34, v174
	v_cmp_gt_u32_e64 s[6:7], s34, v175
	v_cmp_gt_u32_e64 s[8:9], s34, v176
	v_cmp_gt_u32_e64 s[28:29], s34, v177
	v_cmp_gt_u32_e64 s[20:21], s34, v178
	v_cmp_gt_u32_e64 s[0:1], s34, v179
	v_cmp_gt_u32_e64 s[26:27], s34, v180
	v_cmp_gt_u32_e64 s[24:25], s34, v181
	v_cmp_gt_u32_e64 s[82:83], s34, v182
	v_cmp_gt_u32_e64 s[22:23], s34, v183
	v_cmp_gt_u32_e64 s[74:75], s34, v184
	v_cmp_gt_u32_e64 s[18:19], s34, v185
	v_cmp_gt_u32_e64 s[72:73], s34, v186
	v_cmp_gt_u32_e64 s[70:71], s34, v187
	v_cmp_gt_u32_e64 s[68:69], s34, v188
	v_cmp_gt_u32_e64 s[66:67], s34, v189
	v_cmp_gt_u32_e64 s[58:59], s34, v190
	v_cmp_gt_u32_e64 s[54:55], s34, v191
	v_cmp_gt_u32_e64 s[52:53], s34, v192
	v_cmp_gt_u32_e64 s[46:47], s34, v193
	v_cmp_gt_u32_e64 s[38:39], s34, v194
	v_cmp_gt_u32_e64 s[4:5], s34, v195
	s_and_b64 s[50:51], vcc, s[50:51]
	v_readlane_b32 vcc_lo, v255, 10
	v_add_u32_e32 v2, s35, v114
	v_readlane_b32 s34, v253, 27
	v_cmp_lt_i32_e64 s[56:57], s56, v204
	v_readlane_b32 vcc_hi, v255, 11
	v_add_u32_e32 v6, s34, v66
	v_mov_b64_e32 v[54:55], s[94:95]
	s_and_b64 s[56:57], vcc, s[56:57]
	s_mov_b64 s[94:95], s[46:47]
	s_mov_b64 s[46:47], s[54:55]
	s_mov_b64 s[54:55], s[66:67]
	s_mov_b64 s[66:67], s[70:71]
	s_mov_b64 s[70:71], s[18:19]
	s_mov_b64 s[18:19], s[22:23]
	s_mov_b64 s[22:23], s[24:25]
	s_mov_b64 s[24:25], s[0:1]
	s_mov_b64 s[0:1], s[28:29]
	s_mov_b64 s[28:29], s[12:13]
	s_mov_b64 s[12:13], s[14:15]
	s_mov_b64 s[14:15], s[84:85]
	s_mov_b64 s[84:85], s[76:77]
	v_mad_u64_u32 v[6:7], vcc, v6, s89, v[54:55]
	s_mov_b64 s[76:77], s[62:63]
	v_max_i32_e32 v71, 0, v2
	v_max_i32_e32 v52, 0xffffffe0, v2
	v_max_i32_e32 v50, 0xffffffc0, v2
	v_max_i32_e32 v48, 0xffffffa0, v2
	v_max_i32_e32 v46, 0xffffff80, v2
	v_add_u32_e32 v2, s34, v67
	v_lshl_add_u64 v[6:7], v[6:7], 0, s[76:77]
	v_mov_b32_e32 v133, v117
	v_lshl_add_u32 v58, v3, 4, v235
	v_mad_u64_u32 v[2:3], vcc, v2, s89, v[134:135]
	v_lshl_add_u64 v[10:11], v[6:7], 0, v[132:133]
	s_waitcnt lgkmcnt(0)
	s_barrier
; __device__ __forceinline__ f32x4 mfma16(bf16x8 a, bf16x8 b, f32x4 c) { return __builtin_amdgcn_mfma_f32_16x16x32_bf16(a, b, c, 0, 0, 0); }
; template <int BR>
; __device__ __forceinline__ void pattn_group(const bf16* P1, const bf16* VTB, LAS float* O, LAS float* Mx, LAS float* Ls, int t0, int h, int gi, int i16, int g) {
;     ...
;     const bf16* qrow = P1 + (size_t)((mq0 + i16) * dil + r) * P1W + C_AQ + h * 64 + 8 * g;
;     const bf16x8 qf0 = ldfrag(qrow), qf1 = ldfrag(qrow + 32);
;     f32x4 s[5][2];
; #pragma unroll
;     for (int kb = 0; kb < 5; ++kb)
; #pragma unroll
;         for (int hf = 0; hf < 2; ++hf) {
;             int mk = mq0 - 144 + 32 * kb + 8 * (i16 >> 2) + (i16 & 3) + 4 * hf; mk = mk < 0 ? 0 : mk;
;             const bf16* krow = P1 + (size_t)(mk * dil + r) * P1W + C_AK + h * 64 + 8 * g;
;             f32x4 acc = {0.f, 0.f, 0.f, 0.f};
;             acc = mfma16(ldfrag(krow), qf0, acc); acc = mfma16(ldfrag(krow + 32), qf1, acc);
;             s[kb][hf] = acc;
;         }
	global_load_dwordx4 v[30:33], v[2:3], off
	s_nop 0
	global_load_dwordx4 v[2:5], v[2:3], off offset:64
	global_load_dwordx4 v[94:97], v[10:11], off offset:1088
	global_load_dwordx4 v[10:13], v[10:11], off offset:1024
	v_add_u32_e32 v210, s34, v65
	v_mad_u64_u32 v[210:211], vcc, v210, s89, v[54:55]
	v_lshl_add_u64 v[210:211], v[210:211], 0, s[76:77]
	v_lshl_add_u64 v[210:211], v[210:211], 0, v[132:133]
	global_load_dwordx4 v[18:21], v[210:211], off offset:1024
	global_load_dwordx4 v[98:101], v[210:211], off offset:1088
	v_add_u32_e32 v210, s34, v64
	v_mad_u64_u32 v[210:211], vcc, v210, s89, v[54:55]
	v_lshl_add_u64 v[210:211], v[210:211], 0, s[76:77]
	v_lshl_add_u64 v[210:211], v[210:211], 0, v[132:133]
	global_load_dwordx4 v[6:9], v[210:211], off offset:1024
	global_load_dwordx4 v[102:105], v[210:211], off offset:1088
	v_add_u32_e32 v210, s34, v63
	v_mad_u64_u32 v[210:211], vcc, v210, s89, v[54:55]
	v_lshl_add_u64 v[210:211], v[210:211], 0, s[76:77]
	v_lshl_add_u64 v[210:211], v[210:211], 0, v[132:133]
	global_load_dwordx4 v[14:17], v[210:211], off offset:1024
	global_load_dwordx4 v[106:109], v[210:211], off offset:1088
	v_add_u32_e32 v210, s34, v62
	v_mad_u64_u32 v[210:211], vcc, v210, s89, v[54:55]
	v_lshl_add_u64 v[210:211], v[210:211], 0, s[76:77]
	v_lshl_add_u64 v[210:211], v[210:211], 0, v[132:133]
	global_load_dwordx4 v[22:25], v[210:211], off offset:1024
	global_load_dwordx4 v[110:113], v[210:211], off offset:1088
	v_add_u32_e32 v210, s34, v61
	v_mad_u64_u32 v[210:211], vcc, v210, s89, v[54:55]
	v_lshl_add_u64 v[210:211], v[210:211], 0, s[76:77]
	v_lshl_add_u64 v[210:211], v[210:211], 0, v[132:133]
	global_load_dwordx4 v[26:29], v[210:211], off offset:1024
	global_load_dwordx4 v[136:139], v[210:211], off offset:1088
	v_add_u32_e32 v210, s34, v60
	v_mad_u64_u32 v[210:211], vcc, v210, s89, v[54:55]
	v_lshl_add_u64 v[210:211], v[210:211], 0, s[76:77]
	v_lshl_add_u64 v[210:211], v[210:211], 0, v[132:133]
	global_load_dwordx4 v[34:37], v[210:211], off offset:1024
	global_load_dwordx4 v[140:143], v[210:211], off offset:1088
	v_add_u32_e32 v210, s34, v59
	v_mad_u64_u32 v[210:211], vcc, v210, s89, v[54:55]
	v_lshl_add_u64 v[210:211], v[210:211], 0, s[76:77]
	v_lshl_add_u64 v[210:211], v[210:211], 0, v[132:133]
	global_load_dwordx4 v[38:41], v[210:211], off offset:1024
	global_load_dwordx4 v[240:243], v[210:211], off offset:1088
	v_add_u32_e32 v210, s34, v58
	v_mad_u64_u32 v[210:211], vcc, v210, s89, v[54:55]
	v_lshl_add_u64 v[210:211], v[210:211], 0, s[76:77]
	v_lshl_add_u64 v[210:211], v[210:211], 0, v[132:133]
	global_load_dwordx4 v[42:45], v[210:211], off offset:1024
	global_load_dwordx4 v[244:247], v[210:211], off offset:1088
	v_add_u32_e32 v210, s34, v57
	v_mad_u64_u32 v[210:211], vcc, v210, s89, v[54:55]
	v_lshl_add_u64 v[210:211], v[210:211], 0, s[76:77]
	v_lshl_add_u64 v[210:211], v[210:211], 0, v[132:133]
	global_load_dwordx4 v[72:75], v[210:211], off offset:1024
	global_load_dwordx4 v[248:251], v[210:211], off offset:1088
	v_writelane_b32 v254, s2, 50
	v_writelane_b32 v254, s3, 51
	v_writelane_b32 v254, s4, 41
	v_writelane_b32 v254, s5, 42
	s_waitcnt vmcnt(18)
	v_mfma_f32_16x16x32_bf16 v[10:13], v[10:13], v[30:33], 0
	s_waitcnt vmcnt(19)
	v_mfma_f32_16x16x32_bf16 v[10:13], v[94:97], v[2:5], v[10:13]
	s_waitcnt vmcnt(17)
	v_mfma_f32_16x16x32_bf16 v[18:21], v[18:21], v[30:33], 0
	s_waitcnt vmcnt(16)
	v_mfma_f32_16x16x32_bf16 v[18:21], v[98:101], v[2:5], v[18:21]
	s_waitcnt vmcnt(15)
	v_mfma_f32_16x16x32_bf16 v[6:9], v[6:9], v[30:33], 0
	s_waitcnt vmcnt(14)
	v_mfma_f32_16x16x32_bf16 v[6:9], v[102:105], v[2:5], v[6:9]
	s_waitcnt vmcnt(13)
	v_mfma_f32_16x16x32_bf16 v[14:17], v[14:17], v[30:33], 0
	s_waitcnt vmcnt(12)
	v_mfma_f32_16x16x32_bf16 v[14:17], v[106:109], v[2:5], v[14:17]
	s_waitcnt vmcnt(11)
	v_mfma_f32_16x16x32_bf16 v[22:25], v[22:25], v[30:33], 0
	s_waitcnt vmcnt(10)
	v_mfma_f32_16x16x32_bf16 v[22:25], v[110:113], v[2:5], v[22:25]
	s_waitcnt vmcnt(9)
	v_mfma_f32_16x16x32_bf16 v[26:29], v[26:29], v[30:33], 0
	s_waitcnt vmcnt(8)
	v_mfma_f32_16x16x32_bf16 v[26:29], v[136:139], v[2:5], v[26:29]
	s_waitcnt vmcnt(7)
	v_mfma_f32_16x16x32_bf16 v[34:37], v[34:37], v[30:33], 0
	s_waitcnt vmcnt(6)
	v_mfma_f32_16x16x32_bf16 v[34:37], v[140:143], v[2:5], v[34:37]
	s_waitcnt vmcnt(5)
	v_mfma_f32_16x16x32_bf16 v[38:41], v[38:41], v[30:33], 0
	s_waitcnt vmcnt(4)
	v_mfma_f32_16x16x32_bf16 v[38:41], v[240:243], v[2:5], v[38:41]
	s_waitcnt vmcnt(3)
	v_mfma_f32_16x16x32_bf16 v[42:45], v[42:45], v[30:33], 0
	s_waitcnt vmcnt(2)
	v_mfma_f32_16x16x32_bf16 v[42:45], v[244:247], v[2:5], v[42:45]
	s_waitcnt vmcnt(1)
	v_mfma_f32_16x16x32_bf16 v[30:33], v[72:75], v[30:33], 0
	s_waitcnt vmcnt(0)
; __device__ __forceinline__ f32x4 mfma16(bf16x8 a, bf16x8 b, f32x4 c) { return __builtin_amdgcn_mfma_f32_16x16x32_bf16(a, b, c, 0, 0, 0); }
; __device__ __forceinline__ bf16x8 pack8(f32x4 a, f32x4 b) { u32x4 w; w.x = pk2(a[0], a[1]); w.y = pk2(a[2], a[3]); w.z = pk2(b[0], b[1]); w.w = pk2(b[2], b[3]); return __builtin_bit_cast(bf16x8, w); }
; template <int BR>
; __device__ __forceinline__ void pattn_group(const bf16* P1, const bf16* VTB, LAS float* O, LAS float* Mx, LAS float* Ls, int t0, int h, int gi, int i16, int g) {
;     ...
;             acc = mfma16(ldfrag(krow), qf0, acc); acc = mfma16(ldfrag(krow + 32), qf1, acc);
;             s[kb][hf] = acc;
;         }
;     float mx = -1e30f;
; #pragma unroll
;     for (int kb = 0; kb < 5; ++kb)
; #pragma unroll
;         for (int hf = 0; hf < 2; ++hf)
; #pragma unroll
;             for (int e = 0; e < 4; ++e) {
;                 const int c = -144 + 32 * kb + 8 * g + 4 * hf + e, dist = i16 - c;
;                 const bool ok = dist >= 0 && dist <= 128 && (mq0 + c) >= 0;
;                 const float v = ok ? s[kb][hf][e] : -1e30f; s[kb][hf][e] = v; mx = fmaxf(mx, v);
;             }
;     mx = fmaxf(mx, __shfl_xor(mx, 16)); mx = fmaxf(mx, __shfl_xor(mx, 32));
;     ...
;     for (int kb = 0; kb < 5; ++kb) {
;         const bf16x8 pf = pack8(s[kb][0], s[kb][1]);
;         int m0 = mq0 - 144 + 32 * kb + 8 * g; m0 = m0 < 0 ? 0 : m0;
; #pragma unroll
;         for (int dt = 0; dt < 4; ++dt) {
;             const int f = h * 64 + 16 * dt + i16;
;             const bf16* vrow = BR == 0 ? VTB + (size_t)f * MT + m0 : (BR == 1 ? VTB + (size_t)f * 16384 + r * 4096 + m0 : VTB + (size_t)f * 16384 + r * 1024 + m0);
;             ot[dt] = mfma16(ldfrag(vrow), pf, ot[dt]);
	s_nop 1
	v_mfma_f32_16x16x32_bf16 v[2:5], v[248:251], v[2:5], v[30:33]
	v_readlane_b32 s98, v255, 34
	v_readlane_b32 s99, v255, 35
	v_lshlrev_b32_e32 v209, 15, v238
	v_lshl_add_u32 v210, v71, 1, v209
	v_add_u32_e32 v211, 0x80000, v210
	v_add_u32_e32 v224, 0x100000, v210
	v_add_u32_e32 v252, 0x180000, v210
	s_nop 0
	global_load_dwordx4 v[94:97], v210, s[98:99]
	global_load_dwordx4 v[98:101], v211, s[98:99]
	global_load_dwordx4 v[102:105], v224, s[98:99]
	global_load_dwordx4 v[106:109], v252, s[98:99]
	v_lshl_add_u32 v210, v52, 1, v209
	v_add_u32_e32 v210, 64, v210
	v_add_u32_e32 v211, 0x80000, v210
	v_add_u32_e32 v224, 0x100000, v210
	v_add_u32_e32 v252, 0x180000, v210
	global_load_dwordx4 v[110:113], v210, s[98:99]
	global_load_dwordx4 v[136:139], v211, s[98:99]
	global_load_dwordx4 v[140:143], v224, s[98:99]
	global_load_dwordx4 v[240:243], v252, s[98:99]
	v_lshl_add_u32 v210, v50, 1, v209
	v_add_u32_e32 v210, 0x80, v210
	v_add_u32_e32 v211, 0x80000, v210
	global_load_dwordx4 v[244:247], v210, s[98:99]
	global_load_dwordx4 v[248:251], v211, s[98:99]
	v_cndmask_b32_e64 v10, v226, v10, s[84:85]
	v_cndmask_b32_e64 v18, v226, v18, s[12:13]
	v_cndmask_b32_e64 v19, v226, v19, s[28:29]
	v_cndmask_b32_e64 v20, v226, v20, s[30:31]
	v_cndmask_b32_e64 v21, v226, v21, s[10:11]
	v_cndmask_b32_e64 v7, v226, v7, s[2:3]
	v_cndmask_b32_e64 v76, v226, v9, s[8:9]
	v_cndmask_b32_e64 v14, v226, v14, s[0:1]
	v_cndmask_b32_e64 v77, v226, v15, s[20:21]
	v_cndmask_b32_e64 v78, v226, v16, s[24:25]
	v_cndmask_b32_e64 v17, v226, v17, s[26:27]
	v_cndmask_b32_e64 v22, v226, v22, s[22:23]
	v_cndmask_b32_e64 v79, v226, v23, s[82:83]
	v_cndmask_b32_e64 v80, v226, v24, s[18:19]
	v_cndmask_b32_e64 v81, v226, v25, s[74:75]
	v_cndmask_b32_e64 v55, v226, v11, s[92:93]
	v_max3_f32 v11, v10, s65, v55
	v_cndmask_b32_e64 v72, v226, v12, s[14:15]
	v_cndmask_b32_e64 v73, v226, v13, s[16:17]
	v_max3_f32 v11, v11, v72, v73
	v_max3_f32 v11, v11, v18, v19
	v_max3_f32 v11, v11, v20, v21
	v_cndmask_b32_e64 v74, v226, v6, s[96:97]
	v_max3_f32 v6, v11, v74, v7
	v_cndmask_b32_e64 v75, v226, v8, s[6:7]
	v_max3_f32 v6, v6, v75, v76
	v_max3_f32 v6, v6, v14, v77
	v_max3_f32 v6, v6, v78, v17
	v_max3_f32 v6, v6, v22, v79
	v_max3_f32 v6, v6, v80, v81
	v_cndmask_b32_e64 v82, v226, v26, s[70:71]
	v_cndmask_b32_e64 v23, v226, v27, s[72:73]
	v_max3_f32 v6, v6, v82, v23
	v_cndmask_b32_e64 v24, v226, v28, s[66:67]
	v_cndmask_b32_e64 v25, v226, v29, s[68:69]
	v_max3_f32 v6, v6, v24, v25
	v_cndmask_b32_e64 v30, v226, v34, s[54:55]
	v_cndmask_b32_e64 v31, v226, v35, s[58:59]
	v_max3_f32 v6, v6, v30, v31
	v_cndmask_b32_e64 v32, v226, v36, s[46:47]
	v_cndmask_b32_e64 v33, v226, v37, s[52:53]
	v_readlane_b32 s62, v254, 52
	v_max3_f32 v6, v6, v32, v33
	v_cndmask_b32_e64 v54, v226, v38, s[94:95]
	v_cndmask_b32_e64 v39, v226, v39, s[38:39]
	v_readlane_b32 s63, v254, 53
	v_max3_f32 v6, v6, v54, v39
	v_cndmask_b32_e64 v38, v226, v40, s[4:5]
	v_cndmask_b32_e64 v37, v226, v41, s[62:63]
	v_max3_f32 v6, v6, v38, v37
	v_cndmask_b32_e64 v34, v226, v42, s[60:61]
	v_cndmask_b32_e64 v28, v226, v43, s[44:45]
	v_max3_f32 v6, v6, v34, v28
	v_cndmask_b32_e64 v27, v226, v44, s[36:37]
	v_cndmask_b32_e64 v16, v226, v45, s[40:41]
	v_max3_f32 v6, v6, v27, v16
	v_cndmask_b32_e64 v13, v226, v2, s[42:43]
	v_cndmask_b32_e64 v11, v226, v3, s[48:49]
	v_max3_f32 v2, v6, v13, v11
	v_cndmask_b32_e64 v9, v226, v4, s[50:51]
	v_cndmask_b32_e64 v6, v226, v5, s[56:57]
	v_max3_f32 v2, v2, v9, v6
	ds_bpermute_b32 v3, v129, v2
	v_cmp_lt_f32_e32 vcc, s78, v10
	v_readlane_b32 s35, v253, 28
	v_readlane_b32 s34, v255, 34
	v_lshlrev_b32_e32 v56, 14, v238
	s_waitcnt lgkmcnt(0)
	v_max_f32_e32 v3, v3, v3
	v_max_f32_e32 v2, v2, v3
	ds_bpermute_b32 v3, v237, v2
	v_lshlrev_b32_e32 v116, 1, v71
	v_readlane_b32 s35, v255, 35
	v_or_b32_e32 v70, 0x40000, v56
	v_or_b32_e32 v69, 0x80000, v56
	s_waitcnt lgkmcnt(0)
	v_max_f32_e32 v3, v3, v3
	v_max_f32_e32 v36, v2, v3
	v_sub_f32_e32 v2, v10, v36
	v_mul_f32_e32 v2, 0x3fb8aa3b, v2
	v_sub_f32_e32 v3, v55, v36
	v_exp_f32_e32 v2, v2
	v_mul_f32_e32 v3, 0x3fb8aa3b, v3
	v_exp_f32_e32 v3, v3
	v_sub_f32_e32 v41, v54, v36
	v_cndmask_b32_e32 v8, 0, v2, vcc
	v_cmp_lt_f32_e32 vcc, s78, v55
	v_add_f32_e32 v2, 0, v8
	v_mul_f32_e32 v41, 0x3fb8aa3b, v41
	v_cndmask_b32_e32 v12, 0, v3, vcc
	v_sub_f32_e32 v3, v72, v36
	v_mul_f32_e32 v3, 0x3fb8aa3b, v3
	v_exp_f32_e32 v3, v3
	v_cmp_lt_f32_e32 vcc, s78, v72
	v_add_f32_e32 v2, v12, v2
	v_exp_f32_e32 v41, v41
	v_cndmask_b32_e32 v15, 0, v3, vcc
	v_sub_f32_e32 v3, v73, v36
	v_mul_f32_e32 v3, 0x3fb8aa3b, v3
	v_exp_f32_e32 v3, v3
	v_cmp_lt_f32_e32 vcc, s78, v73
	v_add_f32_e32 v2, v15, v2
	v_mov_b32_e32 v55, v117
	v_cndmask_b32_e32 v26, 0, v3, vcc
	v_sub_f32_e32 v3, v18, v36
	v_mul_f32_e32 v3, 0x3fb8aa3b, v3
	v_exp_f32_e32 v3, v3
	v_cmp_lt_f32_e32 vcc, s78, v18
	v_add_f32_e32 v2, v26, v2
	v_or_b32_e32 v68, 0xc0000, v56
	v_cndmask_b32_e32 v29, 0, v3, vcc
	v_sub_f32_e32 v3, v19, v36
	v_mul_f32_e32 v3, 0x3fb8aa3b, v3
	v_exp_f32_e32 v3, v3
	v_cmp_lt_f32_e32 vcc, s78, v19
	v_add_f32_e32 v2, v29, v2
	v_ashrrev_i32_e32 v53, 31, v52
	v_cndmask_b32_e32 v35, 0, v3, vcc
	v_sub_f32_e32 v3, v20, v36
	v_mul_f32_e32 v3, 0x3fb8aa3b, v3
	v_exp_f32_e32 v3, v3
	v_cmp_lt_f32_e32 vcc, s78, v20
	v_add_f32_e32 v2, v35, v2
	v_ashrrev_i32_e32 v51, 31, v50
	v_cndmask_b32_e32 v42, 0, v3, vcc
	v_sub_f32_e32 v3, v21, v36
	v_mul_f32_e32 v3, 0x3fb8aa3b, v3
	v_exp_f32_e32 v3, v3
	v_cmp_lt_f32_e32 vcc, s78, v21
	v_add_f32_e32 v2, v42, v2
	v_ashrrev_i32_e32 v49, 31, v48
	v_cndmask_b32_e32 v43, 0, v3, vcc
	v_add_f32_e32 v3, v43, v2
	v_sub_f32_e32 v2, v74, v36
	v_mul_f32_e32 v2, 0x3fb8aa3b, v2
	v_exp_f32_e32 v2, v2
; template <int BR>
; __device__ __forceinline__ void pattn_group(const bf16* P1, const bf16* VTB, LAS float* O, LAS float* Mx, LAS float* Ls, int t0, int h, int gi, int i16, int g) {
;     ...
;     float l = 0.f;
; #pragma unroll
;     for (int kb = 0; kb < 5; ++kb)
; #pragma unroll
;         for (int hf = 0; hf < 2; ++hf)
; #pragma unroll
;             for (int e = 0; e < 4; ++e) { const float v = s[kb][hf][e]; const float p = v > -1e29f ? __expf(v - mx) : 0.f; s[kb][hf][e] = p; l += p; }
;     l += __shfl_xor(l, 16); l += __shfl_xor(l, 32);
	v_cmp_lt_f32_e32 vcc, s78, v74
	v_ashrrev_i32_e32 v47, 31, v46
	s_nop 0
	v_cndmask_b32_e32 v2, 0, v2, vcc
	v_add_f32_e32 v4, v2, v3
	v_sub_f32_e32 v3, v7, v36
	v_mul_f32_e32 v3, 0x3fb8aa3b, v3
	v_exp_f32_e32 v3, v3
	v_cmp_lt_f32_e32 vcc, s78, v7
	s_nop 1
	v_cndmask_b32_e32 v3, 0, v3, vcc
	v_add_f32_e32 v5, v3, v4
	v_sub_f32_e32 v4, v75, v36
	v_mul_f32_e32 v4, 0x3fb8aa3b, v4
	v_exp_f32_e32 v4, v4
	v_cmp_lt_f32_e32 vcc, s78, v75
	s_nop 1
	v_cndmask_b32_e32 v4, 0, v4, vcc
	v_add_f32_e32 v7, v4, v5
	v_sub_f32_e32 v5, v76, v36
	v_mul_f32_e32 v5, 0x3fb8aa3b, v5
	v_exp_f32_e32 v5, v5
	v_cmp_lt_f32_e32 vcc, s78, v76
	s_nop 1
	v_cndmask_b32_e32 v5, 0, v5, vcc
	v_add_f32_e32 v10, v5, v7
	v_sub_f32_e32 v7, v14, v36
	v_mul_f32_e32 v7, 0x3fb8aa3b, v7
	v_exp_f32_e32 v7, v7
	v_cmp_lt_f32_e32 vcc, s78, v14
	s_nop 1
	v_cndmask_b32_e32 v7, 0, v7, vcc
	v_add_f32_e32 v14, v7, v10
	v_sub_f32_e32 v10, v77, v36
	v_mul_f32_e32 v10, 0x3fb8aa3b, v10
	v_exp_f32_e32 v10, v10
	v_cmp_lt_f32_e32 vcc, s78, v77
	s_nop 1
	v_cndmask_b32_e32 v10, 0, v10, vcc
	v_add_f32_e32 v18, v10, v14
	v_sub_f32_e32 v14, v78, v36
	v_mul_f32_e32 v14, 0x3fb8aa3b, v14
	v_exp_f32_e32 v14, v14
	v_cmp_lt_f32_e32 vcc, s78, v78
	s_nop 1
	v_cndmask_b32_e32 v14, 0, v14, vcc
	v_cmp_lt_f32_e32 vcc, s78, v17
	v_sub_f32_e32 v17, v17, v36
	v_mul_f32_e32 v17, 0x3fb8aa3b, v17
	v_exp_f32_e32 v17, v17
	v_add_f32_e32 v18, v14, v18
	v_cndmask_b32_e32 v17, 0, v17, vcc
	v_add_f32_e32 v19, v17, v18
	v_sub_f32_e32 v18, v22, v36
	v_mul_f32_e32 v18, 0x3fb8aa3b, v18
	v_exp_f32_e32 v18, v18
	v_cmp_lt_f32_e32 vcc, s78, v22
	s_nop 1
	v_cndmask_b32_e32 v18, 0, v18, vcc
	v_add_f32_e32 v20, v18, v19
	v_sub_f32_e32 v19, v79, v36
	v_mul_f32_e32 v19, 0x3fb8aa3b, v19
	v_exp_f32_e32 v19, v19
	v_cmp_lt_f32_e32 vcc, s78, v79
	s_nop 1
	v_cndmask_b32_e32 v19, 0, v19, vcc
	v_add_f32_e32 v21, v19, v20
	v_sub_f32_e32 v20, v80, v36
	v_mul_f32_e32 v20, 0x3fb8aa3b, v20
	v_exp_f32_e32 v20, v20
	v_cmp_lt_f32_e32 vcc, s78, v80
	s_nop 1
	v_cndmask_b32_e32 v20, 0, v20, vcc
	v_add_f32_e32 v22, v20, v21
	v_sub_f32_e32 v21, v81, v36
	v_mul_f32_e32 v21, 0x3fb8aa3b, v21
	v_exp_f32_e32 v21, v21
	v_cmp_lt_f32_e32 vcc, s78, v81
	s_nop 1
	v_cndmask_b32_e32 v21, 0, v21, vcc
	v_add_f32_e32 v40, v21, v22
	v_sub_f32_e32 v22, v82, v36
	v_mul_f32_e32 v22, 0x3fb8aa3b, v22
	v_exp_f32_e32 v22, v22
	v_cmp_lt_f32_e32 vcc, s78, v82
	s_nop 1
	v_cndmask_b32_e32 v22, 0, v22, vcc
	v_cmp_lt_f32_e32 vcc, s78, v23
	v_sub_f32_e32 v23, v23, v36
	v_mul_f32_e32 v23, 0x3fb8aa3b, v23
	v_exp_f32_e32 v23, v23
	v_add_f32_e32 v40, v22, v40
	v_cndmask_b32_e32 v23, 0, v23, vcc
	v_cmp_lt_f32_e32 vcc, s78, v24
	v_sub_f32_e32 v24, v24, v36
	v_mul_f32_e32 v24, 0x3fb8aa3b, v24
	v_exp_f32_e32 v24, v24
	v_add_f32_e32 v40, v23, v40
	v_cndmask_b32_e32 v24, 0, v24, vcc
	v_cmp_lt_f32_e32 vcc, s78, v25
	v_sub_f32_e32 v25, v25, v36
	v_mul_f32_e32 v25, 0x3fb8aa3b, v25
	v_exp_f32_e32 v25, v25
	v_add_f32_e32 v40, v24, v40
	v_cndmask_b32_e32 v25, 0, v25, vcc
	v_cmp_lt_f32_e32 vcc, s78, v30
	v_sub_f32_e32 v30, v30, v36
	v_mul_f32_e32 v30, 0x3fb8aa3b, v30
	v_exp_f32_e32 v30, v30
	v_add_f32_e32 v40, v25, v40
	v_cndmask_b32_e32 v30, 0, v30, vcc
	v_cmp_lt_f32_e32 vcc, s78, v31
	v_sub_f32_e32 v31, v31, v36
	v_mul_f32_e32 v31, 0x3fb8aa3b, v31
	v_exp_f32_e32 v31, v31
	v_add_f32_e32 v40, v30, v40
	v_cndmask_b32_e32 v31, 0, v31, vcc
	v_cmp_lt_f32_e32 vcc, s78, v32
	v_sub_f32_e32 v32, v32, v36
	v_mul_f32_e32 v32, 0x3fb8aa3b, v32
	v_exp_f32_e32 v32, v32
	v_add_f32_e32 v40, v31, v40
	v_cndmask_b32_e32 v32, 0, v32, vcc
	v_cmp_lt_f32_e32 vcc, s78, v33
	v_sub_f32_e32 v33, v33, v36
	v_mul_f32_e32 v33, 0x3fb8aa3b, v33
	v_exp_f32_e32 v33, v33
	v_add_f32_e32 v40, v32, v40
	v_cndmask_b32_e32 v33, 0, v33, vcc
	v_cmp_lt_f32_e32 vcc, s78, v54
	v_add_f32_e32 v40, v33, v40
	v_lshlrev_b32_e32 v54, 1, v70
	v_cndmask_b32_e32 v77, 0, v41, vcc
	v_cmp_lt_f32_e32 vcc, s78, v39
	v_sub_f32_e32 v39, v39, v36
	v_mul_f32_e32 v39, 0x3fb8aa3b, v39
	v_exp_f32_e32 v39, v39
	v_add_f32_e32 v40, v77, v40
	v_cndmask_b32_e32 v78, 0, v39, vcc
	v_cmp_lt_f32_e32 vcc, s78, v38
	v_sub_f32_e32 v38, v38, v36
	v_mul_f32_e32 v38, 0x3fb8aa3b, v38
	v_exp_f32_e32 v38, v38
	v_add_f32_e32 v39, v78, v40
	v_cndmask_b32_e32 v79, 0, v38, vcc
	v_cmp_lt_f32_e32 vcc, s78, v37
	v_sub_f32_e32 v37, v37, v36
	v_mul_f32_e32 v37, 0x3fb8aa3b, v37
	v_exp_f32_e32 v37, v37
	v_add_f32_e32 v38, v79, v39
	v_cndmask_b32_e32 v80, 0, v37, vcc
	v_cmp_lt_f32_e32 vcc, s78, v34
	v_sub_f32_e32 v34, v34, v36
	v_mul_f32_e32 v34, 0x3fb8aa3b, v34
	v_exp_f32_e32 v34, v34
	v_add_f32_e32 v37, v80, v38
	v_cndmask_b32_e32 v39, 0, v34, vcc
	v_cmp_lt_f32_e32 vcc, s78, v28
	v_sub_f32_e32 v28, v28, v36
	v_mul_f32_e32 v28, 0x3fb8aa3b, v28
	v_exp_f32_e32 v28, v28
	v_add_f32_e32 v34, v39, v37
	v_cndmask_b32_e32 v40, 0, v28, vcc
	v_cmp_lt_f32_e32 vcc, s78, v27
	v_sub_f32_e32 v27, v27, v36
	v_mul_f32_e32 v27, 0x3fb8aa3b, v27
	v_exp_f32_e32 v27, v27
	v_add_f32_e32 v28, v40, v34
	v_lshlrev_b32_e32 v34, 15, v238
	v_cndmask_b32_e32 v41, 0, v27, vcc
	v_cmp_lt_f32_e32 vcc, s78, v16
	v_sub_f32_e32 v16, v16, v36
	v_mul_f32_e32 v16, 0x3fb8aa3b, v16
	v_exp_f32_e32 v16, v16
	v_add_f32_e32 v27, v41, v28
	v_cndmask_b32_e32 v72, 0, v16, vcc
	v_cmp_lt_f32_e32 vcc, s78, v13
	v_sub_f32_e32 v13, v13, v36
	v_mul_f32_e32 v13, 0x3fb8aa3b, v13
	v_exp_f32_e32 v13, v13
	v_add_f32_e32 v16, v72, v27
	v_cndmask_b32_e32 v73, 0, v13, vcc
	v_cmp_lt_f32_e32 vcc, s78, v11
	v_sub_f32_e32 v11, v11, v36
	v_mul_f32_e32 v11, 0x3fb8aa3b, v11
	v_exp_f32_e32 v11, v11
	v_add_f32_e32 v13, v73, v16
	v_cndmask_b32_e32 v74, 0, v11, vcc
	v_cmp_lt_f32_e32 vcc, s78, v9
	v_sub_f32_e32 v9, v9, v36
	v_mul_f32_e32 v9, 0x3fb8aa3b, v9
	v_exp_f32_e32 v9, v9
	v_add_f32_e32 v11, v74, v13
	v_cndmask_b32_e32 v75, 0, v9, vcc
	v_cmp_lt_f32_e32 vcc, s78, v6
	v_sub_f32_e32 v6, v6, v36
	v_mul_f32_e32 v6, 0x3fb8aa3b, v6
	v_exp_f32_e32 v6, v6
	v_add_f32_e32 v9, v75, v11
	v_cndmask_b32_e32 v76, 0, v6, vcc
	v_add_f32_e32 v6, v76, v9
	ds_bpermute_b32 v9, v129, v6
	s_mov_b64 vcc, 0x80
	s_waitcnt lgkmcnt(0)
; __device__ __forceinline__ f32x4 mfma16(bf16x8 a, bf16x8 b, f32x4 c) { return __builtin_amdgcn_mfma_f32_16x16x32_bf16(a, b, c, 0, 0, 0); }
; __device__ __forceinline__ bf16x8 pack8(f32x4 a, f32x4 b) { u32x4 w; w.x = pk2(a[0], a[1]); w.y = pk2(a[2], a[3]); w.z = pk2(b[0], b[1]); w.w = pk2(b[2], b[3]); return __builtin_bit_cast(bf16x8, w); }
; template <int BR>
; __device__ __forceinline__ void pattn_group(const bf16* P1, const bf16* VTB, LAS float* O, LAS float* Mx, LAS float* Ls, int t0, int h, int gi, int i16, int g) {
;     ...
; #pragma unroll
;     for (int kb = 0; kb < 5; ++kb) {
;         const bf16x8 pf = pack8(s[kb][0], s[kb][1]);
;         int m0 = mq0 - 144 + 32 * kb + 8 * g; m0 = m0 < 0 ? 0 : m0;
; #pragma unroll
;         for (int dt = 0; dt < 4; ++dt) {
;             const int f = h * 64 + 16 * dt + i16;
;             const bf16* vrow = BR == 0 ? VTB + (size_t)f * MT + m0 : (BR == 1 ? VTB + (size_t)f * 16384 + r * 4096 + m0 : VTB + (size_t)f * 16384 + r * 1024 + m0);
;             ot[dt] = mfma16(ldfrag(vrow), pf, ot[dt]);
;         }
;     }
	v_add_f32_e32 v37, v6, v9
	v_bfe_u32 v6, v8, 16, 1
	v_add3_u32 v6, v8, v6, s79
	v_bfe_u32 v8, v12, 16, 1
	v_lshrrev_b32_e32 v6, 16, v6
	v_add3_u32 v8, v12, v8, s79
	v_and_or_b32 v82, v8, s80, v6
	v_bfe_u32 v6, v15, 16, 1
	v_add3_u32 v6, v15, v6, s79
	v_bfe_u32 v8, v26, 16, 1
	v_lshrrev_b32_e32 v6, 16, v6
	v_add3_u32 v8, v26, v8, s79
	v_and_or_b32 v83, v8, s80, v6
	v_bfe_u32 v6, v29, 16, 1
	v_add3_u32 v6, v29, v6, s79
	v_bfe_u32 v8, v35, 16, 1
	v_lshrrev_b32_e32 v6, 16, v6
	v_add3_u32 v8, v35, v8, s79
	v_and_or_b32 v84, v8, s80, v6
	v_bfe_u32 v6, v42, 16, 1
	v_add3_u32 v6, v42, v6, s79
	v_bfe_u32 v8, v43, 16, 1
	v_lshrrev_b32_e32 v6, 16, v6
	v_add3_u32 v8, v43, v8, s79
	v_and_or_b32 v85, v8, s80, v6
	v_lshl_add_u64 v[8:9], s[34:35], 0, v[116:117]
	v_mov_b32_e32 v35, v117
	v_lshl_add_u64 v[12:13], v[8:9], 0, v[34:35]
	s_nop 0
	v_lshl_add_u64 v[12:13], v[8:9], 0, v[54:55]
	s_nop 0
	s_nop 0
	s_waitcnt vmcnt(8)
	v_mfma_f32_16x16x32_bf16 v[86:89], v[98:101], v[82:85], 0
	v_lshlrev_b32_e32 v44, 1, v69
	v_mov_b32_e32 v45, v117
	v_lshlrev_b32_e32 v42, 1, v68
	v_mov_b32_e32 v43, v117
	v_lshl_add_u64 v[12:13], v[8:9], 0, v[44:45]
	v_lshl_add_u64 v[8:9], v[8:9], 0, v[42:43]
	s_nop 0
	s_nop 0
	v_bfe_u32 v6, v2, 16, 1
	v_add3_u32 v2, v2, v6, s79
	v_bfe_u32 v6, v3, 16, 1
	v_lshrrev_b32_e32 v2, 16, v2
	v_add3_u32 v3, v3, v6, s79
	s_waitcnt vmcnt(9)
	v_mfma_f32_16x16x32_bf16 v[26:29], v[94:97], v[82:85], 0
	ds_bpermute_b32 v38, v237, v37
	s_nop 0
	s_waitcnt vmcnt(7)
	v_mfma_f32_16x16x32_bf16 v[90:93], v[102:105], v[82:85], 0
	s_nop 0
	s_waitcnt vmcnt(6)
	v_mfma_f32_16x16x32_bf16 v[68:71], v[106:109], v[82:85], 0
	v_lshl_add_u32 v210, v50, 1, v209
	v_add_u32_e32 v210, 0x80, v210
	v_add_u32_e32 v211, 0x100000, v210
	global_load_dwordx4 v[94:97], v211, s[98:99]
	v_add_u32_e32 v211, 0x180000, v210
	global_load_dwordx4 v[98:101], v211, s[98:99]
	v_lshl_add_u32 v210, v48, 1, v209
	v_add_u32_e32 v210, 0xc0, v210
	global_load_dwordx4 v[102:105], v210, s[98:99]
	v_add_u32_e32 v211, 0x80000, v210
	global_load_dwordx4 v[106:109], v211, s[98:99]
	v_and_or_b32 v82, v3, s80, v2
	v_bfe_u32 v2, v4, 16, 1
	v_add3_u32 v2, v4, v2, s79
	v_bfe_u32 v3, v5, 16, 1
	v_lshrrev_b32_e32 v2, 16, v2
	v_add3_u32 v3, v5, v3, s79
	v_and_or_b32 v83, v3, s80, v2
	v_bfe_u32 v2, v7, 16, 1
	v_add3_u32 v2, v7, v2, s79
	v_bfe_u32 v3, v10, 16, 1
	v_lshrrev_b32_e32 v2, 16, v2
	v_add3_u32 v3, v10, v3, s79
	v_and_or_b32 v84, v3, s80, v2
	v_bfe_u32 v2, v14, 16, 1
	v_add3_u32 v2, v14, v2, s79
	v_bfe_u32 v3, v17, 16, 1
	v_lshrrev_b32_e32 v2, 16, v2
	v_add3_u32 v3, v17, v3, s79
	v_and_or_b32 v85, v3, s80, v2
	v_lshl_add_u64 v[2:3], v[52:53], 1, s[34:35]
	v_lshl_add_u64 v[14:15], v[2:3], 0, 64
	v_lshl_add_u64 v[2:3], v[2:3], 0, v[34:35]
	s_nop 0
	v_lshl_add_u64 v[6:7], v[14:15], 0, v[54:55]
	v_lshl_add_u64 v[10:11], v[14:15], 0, v[44:45]
	v_lshl_add_u64 v[14:15], v[14:15], 0, v[42:43]
	s_nop 0
	s_nop 0
	s_nop 0
	s_nop 0
	s_waitcnt vmcnt(9)
	v_mfma_f32_16x16x32_bf16 v[2:5], v[110:113], v[82:85], v[26:29]
	s_nop 2
	v_bfe_u32 v26, v18, 16, 1
	v_add3_u32 v18, v18, v26, s79
	v_bfe_u32 v26, v19, 16, 1
	v_lshrrev_b32_e32 v18, 16, v18
	v_add3_u32 v19, v19, v26, s79
	v_and_or_b32 v18, v19, s80, v18
	v_bfe_u32 v19, v20, 16, 1
	v_add3_u32 v19, v20, v19, s79
	v_bfe_u32 v20, v21, 16, 1
	v_lshrrev_b32_e32 v19, 16, v19
	v_add3_u32 v20, v21, v20, s79
	v_and_or_b32 v19, v20, s80, v19
	v_bfe_u32 v20, v22, 16, 1
	v_add3_u32 v20, v22, v20, s79
	v_bfe_u32 v21, v23, 16, 1
	v_lshrrev_b32_e32 v20, 16, v20
	v_add3_u32 v21, v23, v21, s79
	v_and_or_b32 v20, v21, s80, v20
	v_bfe_u32 v21, v24, 16, 1
	v_add3_u32 v21, v24, v21, s79
	v_bfe_u32 v22, v25, 16, 1
	v_lshrrev_b32_e32 v21, 16, v21
	v_add3_u32 v22, v25, v22, s79
	v_and_or_b32 v21, v22, s80, v21
	v_lshl_add_u64 v[22:23], v[50:51], 1, s[34:35]
	s_nop 0
	s_waitcnt vmcnt(6)
	v_mfma_f32_16x16x32_bf16 v[14:17], v[240:243], v[82:85], v[68:71]
	s_nop 0
	s_nop 1
	v_lshl_add_u64 v[68:69], v[22:23], 0, vcc
	v_lshl_add_u64 v[22:23], v[22:23], 0, v[34:35]
	s_nop 0
	s_nop 0
	s_waitcnt vmcnt(8)
	v_mfma_f32_16x16x32_bf16 v[6:9], v[136:139], v[82:85], v[86:89]
	s_mov_b64 vcc, 0xc0
	s_nop 0
	s_waitcnt vmcnt(5)
	v_mfma_f32_16x16x32_bf16 v[2:5], v[244:247], v[18:21], v[2:5]
	v_lshl_add_u64 v[22:23], v[68:69], 0, v[54:55]
	s_nop 0
	s_nop 0
	s_waitcnt vmcnt(4)
	v_mfma_f32_16x16x32_bf16 v[22:25], v[248:251], v[18:21], v[6:9]
	v_lshl_add_u32 v210, v46, 1, v209
	v_add_u32_e32 v210, 0x100, v210
	v_add_u32_e32 v211, 0x100000, v210
	global_load_dwordx4 v[244:247], v211, s[98:99]
	v_add_u32_e32 v211, 0x180000, v210
	global_load_dwordx4 v[248:251], v211, s[98:99]
	s_nop 2
	v_lshl_add_u64 v[6:7], v[68:69], 0, v[44:45]
	s_nop 0
	s_waitcnt vmcnt(9)
	v_mfma_f32_16x16x32_bf16 v[10:13], v[140:143], v[82:85], v[90:93]
	v_lshl_add_u32 v210, v48, 1, v209
	v_add_u32_e32 v210, 0xc0, v210
	v_add_u32_e32 v211, 0x100000, v210
	global_load_dwordx4 v[110:113], v211, s[98:99]
	v_add_u32_e32 v211, 0x180000, v210
	global_load_dwordx4 v[136:139], v211, s[98:99]
	v_lshl_add_u32 v210, v46, 1, v209
	v_add_u32_e32 v210, 0x100, v210
	global_load_dwordx4 v[140:143], v210, s[98:99]
	v_add_u32_e32 v211, 0x80000, v210
	global_load_dwordx4 v[240:243], v211, s[98:99]
	s_nop 0
	s_waitcnt vmcnt(9)
	v_mfma_f32_16x16x32_bf16 v[26:29], v[94:97], v[18:21], v[10:13]
	v_lshl_add_u64 v[6:7], v[68:69], 0, v[42:43]
	s_nop 0
	s_nop 0
	s_waitcnt vmcnt(8)
; #define LAS __attribute__((address_space(3)))
; __device__ __forceinline__ f32x4 mfma16(bf16x8 a, bf16x8 b, f32x4 c) { return __builtin_amdgcn_mfma_f32_16x16x32_bf16(a, b, c, 0, 0, 0); }
; __device__ __forceinline__ bf16x8 pack8(f32x4 a, f32x4 b) { u32x4 w; w.x = pk2(a[0], a[1]); w.y = pk2(a[2], a[3]); w.z = pk2(b[0], b[1]); w.w = pk2(b[2], b[3]); return __builtin_bit_cast(bf16x8, w); }
; template <int BR>
; __device__ __forceinline__ void pattn_group(const bf16* P1, const bf16* VTB, LAS float* O, LAS float* Mx, LAS float* Ls, int t0, int h, int gi, int i16, int g) {
;     ...
;     for (int kb = 0; kb < 5; ++kb) {
;         const bf16x8 pf = pack8(s[kb][0], s[kb][1]);
;         int m0 = mq0 - 144 + 32 * kb + 8 * g; m0 = m0 < 0 ? 0 : m0;
; #pragma unroll
;         for (int dt = 0; dt < 4; ++dt) {
;             const int f = h * 64 + 16 * dt + i16;
;             const bf16* vrow = BR == 0 ? VTB + (size_t)f * MT + m0 : (BR == 1 ? VTB + (size_t)f * 16384 + r * 4096 + m0 : VTB + (size_t)f * 16384 + r * 1024 + m0);
;             ot[dt] = mfma16(ldfrag(vrow), pf, ot[dt]);
;         }
;     }
;     const int ql = ql0 + dil * i16;
;     LAS float* orow = O + ql * 68 + 4 * g;
;     if (BR == 0) {
; #pragma unroll
;         for (int dt = 0; dt < 4; ++dt) *(LAS f32x4*)(orow + 16 * dt) = ot[dt];
;         if (g == 0) { Mx[ql] = mx; Ls[ql] = l; }
;     } else {
;         const float Mo = Mx[ql], Lo = Ls[ql], Mn = fmaxf(Mo, mx), fo = __expf(Mo - Mn), fn = __expf(mx - Mn);
; #pragma unroll
;         for (int dt = 0; dt < 4; ++dt) { const f32x4 v = *(const LAS f32x4*)(orow + 16 * dt); *(LAS f32x4*)(orow + 16 * dt) = v * fo + ot[dt] * fn; }
;         if (g == 0) { Mx[ql] = Mn; Ls[ql] = Lo * fo + l * fn; }
;     }
	v_mfma_f32_16x16x32_bf16 v[14:17], v[98:101], v[18:21], v[14:17]
	v_bfe_u32 v6, v30, 16, 1
	v_add3_u32 v6, v30, v6, s79
	v_bfe_u32 v7, v31, 16, 1
	v_lshrrev_b32_e32 v6, 16, v6
	v_add3_u32 v7, v31, v7, s79
	v_and_or_b32 v30, v7, s80, v6
	v_bfe_u32 v6, v32, 16, 1
	v_add3_u32 v6, v32, v6, s79
	v_bfe_u32 v7, v33, 16, 1
	v_lshrrev_b32_e32 v6, 16, v6
	v_add3_u32 v7, v33, v7, s79
	v_and_or_b32 v31, v7, s80, v6
	v_bfe_u32 v6, v77, 16, 1
	v_add3_u32 v6, v77, v6, s79
	v_bfe_u32 v7, v78, 16, 1
	v_lshrrev_b32_e32 v6, 16, v6
	v_add3_u32 v7, v78, v7, s79
	v_and_or_b32 v32, v7, s80, v6
	v_bfe_u32 v6, v79, 16, 1
	v_add3_u32 v6, v79, v6, s79
	v_bfe_u32 v7, v80, 16, 1
	v_lshrrev_b32_e32 v6, 16, v6
	v_add3_u32 v7, v80, v7, s79
	v_and_or_b32 v33, v7, s80, v6
	v_lshl_add_u64 v[6:7], v[48:49], 1, s[34:35]
	v_lshl_add_u64 v[68:69], v[6:7], 0, vcc
	v_lshl_add_u64 v[6:7], v[6:7], 0, v[34:35]
	s_nop 0
	s_nop 0
	s_waitcnt vmcnt(7)
	v_mfma_f32_16x16x32_bf16 v[6:9], v[102:105], v[30:33], v[2:5]
	s_nop 2
	v_lshl_add_u64 v[2:3], v[68:69], 0, v[54:55]
	s_nop 0
	s_nop 0
	s_waitcnt vmcnt(6)
	v_mfma_f32_16x16x32_bf16 v[10:13], v[106:109], v[30:33], v[22:25]
	v_lshl_add_u64 v[2:3], v[68:69], 0, v[44:45]
	s_nop 0
	s_nop 0
	s_waitcnt vmcnt(3)
	v_mfma_f32_16x16x32_bf16 v[18:21], v[110:113], v[30:33], v[26:29]
	v_lshl_add_u64 v[2:3], v[68:69], 0, v[42:43]
	s_nop 0
	s_nop 0
	s_waitcnt vmcnt(2)
	v_mfma_f32_16x16x32_bf16 v[2:5], v[136:139], v[30:33], v[14:17]
	s_nop 2
	v_bfe_u32 v14, v39, 16, 1
	v_add3_u32 v14, v39, v14, s79
	v_bfe_u32 v15, v40, 16, 1
	v_lshrrev_b32_e32 v14, 16, v14
	v_add3_u32 v15, v40, v15, s79
	v_and_or_b32 v22, v15, s80, v14
	v_bfe_u32 v14, v41, 16, 1
	v_add3_u32 v14, v41, v14, s79
	v_bfe_u32 v15, v72, 16, 1
	v_lshrrev_b32_e32 v14, 16, v14
	v_add3_u32 v15, v72, v15, s79
	v_and_or_b32 v23, v15, s80, v14
	v_bfe_u32 v14, v73, 16, 1
	v_add3_u32 v14, v73, v14, s79
	v_bfe_u32 v15, v74, 16, 1
	v_lshrrev_b32_e32 v14, 16, v14
	v_add3_u32 v15, v74, v15, s79
	v_and_or_b32 v24, v15, s80, v14
	v_bfe_u32 v14, v75, 16, 1
	v_add3_u32 v14, v75, v14, s79
	v_bfe_u32 v15, v76, 16, 1
	v_lshrrev_b32_e32 v14, 16, v14
	v_add3_u32 v15, v76, v15, s79
	v_and_or_b32 v25, v15, s80, v14
	v_lshl_add_u64 v[14:15], v[46:47], 1, s[34:35]
	s_mov_b64 s[34:35], 0x100
	v_lshl_add_u64 v[26:27], v[14:15], 0, s[34:35]
	v_lshl_add_u64 v[14:15], v[14:15], 0, v[34:35]
	s_nop 0
	s_nop 0
	s_waitcnt vmcnt(1)
	v_mfma_f32_16x16x32_bf16 v[14:17], v[140:143], v[22:25], v[6:9]
	s_nop 2
	v_lshl_add_u64 v[6:7], v[26:27], 0, v[54:55]
	s_nop 0
	s_nop 0
	s_waitcnt vmcnt(0)
	v_mfma_f32_16x16x32_bf16 v[10:13], v[240:243], v[22:25], v[10:13]
	v_lshl_add_u64 v[6:7], v[26:27], 0, v[44:45]
	s_nop 0
	s_nop 0
	s_waitcnt vmcnt(5)
	v_mfma_f32_16x16x32_bf16 v[6:9], v[244:247], v[22:25], v[18:21]
	s_nop 2
	v_lshl_add_u64 v[18:19], v[26:27], 0, v[42:43]
	s_nop 0
	s_nop 0
	s_waitcnt vmcnt(4)
	v_mfma_f32_16x16x32_bf16 v[2:5], v[248:251], v[22:25], v[2:5]
	ds_read_b32 v18, v216
	ds_read_b32 v19, v217
	ds_read_b128 v[22:25], v123
	s_waitcnt lgkmcnt(2)
	v_max_f32_e32 v20, v18, v18
	v_max_f32_e32 v21, v20, v36
	v_sub_f32_e32 v20, v36, v21
	v_sub_f32_e32 v18, v18, v21
	v_mul_f32_e32 v20, 0x3fb8aa3b, v20
	v_mul_f32_e32 v18, 0x3fb8aa3b, v18
	v_exp_f32_e32 v20, v20
	v_exp_f32_e32 v18, v18
	v_pk_mul_f32 v[16:17], v[16:17], v[20:21] op_sel_hi:[1,0]
	v_pk_mul_f32 v[14:15], v[14:15], v[20:21] op_sel_hi:[1,0]
	s_waitcnt lgkmcnt(0)
	v_pk_fma_f32 v[16:17], v[24:25], v[18:19], v[16:17] op_sel_hi:[1,0,1]
	v_pk_fma_f32 v[14:15], v[22:23], v[18:19], v[14:15] op_sel_hi:[1,0,1]
	ds_write_b128 v123, v[14:17]
	ds_read_b128 v[14:17], v123 offset:64
	v_pk_mul_f32 v[12:13], v[12:13], v[20:21] op_sel_hi:[1,0]
	v_pk_mul_f32 v[10:11], v[10:11], v[20:21] op_sel_hi:[1,0]
	v_pk_mul_f32 v[8:9], v[8:9], v[20:21] op_sel_hi:[1,0]
	v_pk_mul_f32 v[6:7], v[6:7], v[20:21] op_sel_hi:[1,0]
	s_waitcnt lgkmcnt(0)
	v_pk_fma_f32 v[12:13], v[16:17], v[18:19], v[12:13] op_sel_hi:[1,0,1]
	v_pk_fma_f32 v[10:11], v[14:15], v[18:19], v[10:11] op_sel_hi:[1,0,1]
	ds_write_b128 v123, v[10:13] offset:64
	ds_read_b128 v[10:13], v123 offset:128
	s_waitcnt lgkmcnt(0)
	v_pk_fma_f32 v[8:9], v[18:19], v[12:13], v[8:9] op_sel_hi:[0,1,1]
	v_pk_fma_f32 v[6:7], v[18:19], v[10:11], v[6:7] op_sel_hi:[0,1,1]
	ds_write_b128 v123, v[6:9] offset:128
	ds_read_b128 v[6:9], v123 offset:192
	s_waitcnt lgkmcnt(0)
	v_pk_mul_f32 v[6:7], v[18:19], v[6:7] op_sel_hi:[0,1]
	v_pk_mul_f32 v[8:9], v[18:19], v[8:9] op_sel_hi:[0,1]
	v_pk_fma_f32 v[4:5], v[4:5], v[20:21], v[8:9] op_sel_hi:[1,0,1]
	v_pk_fma_f32 v[2:3], v[2:3], v[20:21], v[6:7] op_sel_hi:[1,0,1]
	ds_write_b128 v123, v[2:5] offset:192
	s_mov_b64 vcc, exec
	v_readlane_b32 s34, v254, 37
	v_readlane_b32 s35, v254, 38
	s_and_b64 s[34:35], vcc, s[34:35]
	s_mov_b64 exec, s[34:35]
	s_cbranch_execz .LBB0_984
	v_add_f32_e32 v2, v37, v38
	v_mul_f32_e32 v2, v20, v2
	v_fmac_f32_e32 v2, v19, v18
	ds_write_b32 v216, v21
	ds_write_b32 v217, v2
; __device__ __forceinline__ f32x4 mfma16(bf16x8 a, bf16x8 b, f32x4 c) { return __builtin_amdgcn_mfma_f32_16x16x32_bf16(a, b, c, 0, 0, 0); }
; template <int BR>
; __device__ __forceinline__ void pattn_group(const bf16* P1, const bf16* VTB, LAS float* O, LAS float* Mx, LAS float* Ls, int t0, int h, int gi, int i16, int g) {
;     ...
;     const bf16* qrow = P1 + (size_t)((mq0 + i16) * dil + r) * P1W + C_AQ + h * 64 + 8 * g;
;     const bf16x8 qf0 = ldfrag(qrow), qf1 = ldfrag(qrow + 32);
;     f32x4 s[5][2];
; #pragma unroll
;     for (int kb = 0; kb < 5; ++kb)
; #pragma unroll
;         for (int hf = 0; hf < 2; ++hf) {
;             int mk = mq0 - 144 + 32 * kb + 8 * (i16 >> 2) + (i16 & 3) + 4 * hf; mk = mk < 0 ? 0 : mk;
;             const bf16* krow = P1 + (size_t)(mk * dil + r) * P1W + C_AK + h * 64 + 8 * g;
;             f32x4 acc = {0.f, 0.f, 0.f, 0.f};
;             acc = mfma16(ldfrag(krow), qf0, acc); acc = mfma16(ldfrag(krow + 32), qf1, acc);
;             s[kb][hf] = acc;
;         }
.LBB0_984:
	s_or_b64 exec, exec, vcc
	v_readlane_b32 vcc_lo, v255, 38
	v_readlane_b32 s2, v254, 50
	v_readlane_b32 s3, v254, 51
	v_add_u32_e32 v2, vcc_lo, v67
	v_mad_u64_u32 v[2:3], s[34:35], v2, s89, v[134:135]
	v_readlane_b32 s34, v254, 39
	v_readlane_b32 s35, v254, 40
	global_load_dwordx4 v[38:41], v[2:3], off
	global_load_dwordx4 v[68:71], v[2:3], off offset:64
	v_add_u32_e32 v210, vcc_lo, v66
	v_mov_b64_e32 v[66:67], s[34:35]
	v_mad_u64_u32 v[210:211], s[34:35], v210, s89, v[66:67]
	v_lshl_add_u64 v[210:211], v[210:211], 0, s[76:77]
	v_lshl_add_u64 v[210:211], v[210:211], 0, v[132:133]
	global_load_dwordx4 v[26:29], v[210:211], off offset:1024
	global_load_dwordx4 v[94:97], v[210:211], off offset:1088
	v_add_u32_e32 v210, vcc_lo, v65
	v_mad_u64_u32 v[210:211], s[34:35], v210, s89, v[66:67]
	v_lshl_add_u64 v[210:211], v[210:211], 0, s[76:77]
	v_lshl_add_u64 v[210:211], v[210:211], 0, v[132:133]
	global_load_dwordx4 v[2:5], v[210:211], off offset:1024
	global_load_dwordx4 v[98:101], v[210:211], off offset:1088
	v_add_u32_e32 v210, vcc_lo, v64
	v_mad_u64_u32 v[210:211], s[34:35], v210, s89, v[66:67]
	v_lshl_add_u64 v[210:211], v[210:211], 0, s[76:77]
	v_lshl_add_u64 v[210:211], v[210:211], 0, v[132:133]
	global_load_dwordx4 v[6:9], v[210:211], off offset:1024
	global_load_dwordx4 v[102:105], v[210:211], off offset:1088
	v_add_u32_e32 v210, vcc_lo, v63
	v_mad_u64_u32 v[210:211], s[34:35], v210, s89, v[66:67]
	v_lshl_add_u64 v[210:211], v[210:211], 0, s[76:77]
	v_lshl_add_u64 v[210:211], v[210:211], 0, v[132:133]
	global_load_dwordx4 v[10:13], v[210:211], off offset:1024
	global_load_dwordx4 v[106:109], v[210:211], off offset:1088
	v_add_u32_e32 v210, vcc_lo, v62
	v_mad_u64_u32 v[210:211], s[34:35], v210, s89, v[66:67]
	v_lshl_add_u64 v[210:211], v[210:211], 0, s[76:77]
	v_lshl_add_u64 v[210:211], v[210:211], 0, v[132:133]
	global_load_dwordx4 v[14:17], v[210:211], off offset:1024
	global_load_dwordx4 v[110:113], v[210:211], off offset:1088
	v_add_u32_e32 v210, vcc_lo, v61
	v_mad_u64_u32 v[210:211], s[34:35], v210, s89, v[66:67]
	v_lshl_add_u64 v[210:211], v[210:211], 0, s[76:77]
	v_lshl_add_u64 v[210:211], v[210:211], 0, v[132:133]
	global_load_dwordx4 v[18:21], v[210:211], off offset:1024
	global_load_dwordx4 v[136:139], v[210:211], off offset:1088
	v_add_u32_e32 v210, vcc_lo, v60
	v_mad_u64_u32 v[210:211], s[34:35], v210, s89, v[66:67]
	v_lshl_add_u64 v[210:211], v[210:211], 0, s[76:77]
	v_lshl_add_u64 v[210:211], v[210:211], 0, v[132:133]
	global_load_dwordx4 v[22:25], v[210:211], off offset:1024
	global_load_dwordx4 v[140:143], v[210:211], off offset:1088
	v_add_u32_e32 v210, vcc_lo, v59
	v_mad_u64_u32 v[210:211], s[34:35], v210, s89, v[66:67]
	v_lshl_add_u64 v[210:211], v[210:211], 0, s[76:77]
	v_lshl_add_u64 v[210:211], v[210:211], 0, v[132:133]
	global_load_dwordx4 v[30:33], v[210:211], off offset:1024
	global_load_dwordx4 v[240:243], v[210:211], off offset:1088
	v_add_u32_e32 v210, vcc_lo, v58
	v_mad_u64_u32 v[210:211], s[34:35], v210, s89, v[66:67]
	v_lshl_add_u64 v[210:211], v[210:211], 0, s[76:77]
	v_lshl_add_u64 v[210:211], v[210:211], 0, v[132:133]
	global_load_dwordx4 v[34:37], v[210:211], off offset:1024
	global_load_dwordx4 v[244:247], v[210:211], off offset:1088
	v_add_u32_e32 v210, vcc_lo, v57
	v_mad_u64_u32 v[210:211], s[34:35], v210, s89, v[66:67]
	v_lshl_add_u64 v[210:211], v[210:211], 0, s[76:77]
	v_lshl_add_u64 v[210:211], v[210:211], 0, v[132:133]
	global_load_dwordx4 v[58:61], v[210:211], off offset:1024
	global_load_dwordx4 v[248:251], v[210:211], off offset:1088
	s_waitcnt vmcnt(19)
	v_mfma_f32_16x16x32_bf16 v[26:29], v[26:29], v[38:41], 0
	s_waitcnt vmcnt(18)
	v_mfma_f32_16x16x32_bf16 v[26:29], v[94:97], v[68:71], v[26:29]
	s_waitcnt vmcnt(17)
	v_mfma_f32_16x16x32_bf16 v[2:5], v[2:5], v[38:41], 0
	s_waitcnt vmcnt(16)
	v_mfma_f32_16x16x32_bf16 v[2:5], v[98:101], v[68:71], v[2:5]
	s_waitcnt vmcnt(15)
	v_mfma_f32_16x16x32_bf16 v[6:9], v[6:9], v[38:41], 0
	s_waitcnt vmcnt(14)
	v_mfma_f32_16x16x32_bf16 v[6:9], v[102:105], v[68:71], v[6:9]
	s_waitcnt vmcnt(13)
	v_mfma_f32_16x16x32_bf16 v[10:13], v[10:13], v[38:41], 0
	s_waitcnt vmcnt(12)
	v_mfma_f32_16x16x32_bf16 v[10:13], v[106:109], v[68:71], v[10:13]
	s_waitcnt vmcnt(11)
	v_mfma_f32_16x16x32_bf16 v[14:17], v[14:17], v[38:41], 0
	s_waitcnt vmcnt(10)
	v_mfma_f32_16x16x32_bf16 v[14:17], v[110:113], v[68:71], v[14:17]
	s_waitcnt vmcnt(9)
	v_mfma_f32_16x16x32_bf16 v[18:21], v[18:21], v[38:41], 0
	s_waitcnt vmcnt(8)
	v_mfma_f32_16x16x32_bf16 v[18:21], v[136:139], v[68:71], v[18:21]
	s_waitcnt vmcnt(7)
	v_mfma_f32_16x16x32_bf16 v[22:25], v[22:25], v[38:41], 0
	s_waitcnt vmcnt(6)
	v_mfma_f32_16x16x32_bf16 v[22:25], v[140:143], v[68:71], v[22:25]
	s_waitcnt vmcnt(5)
	v_mfma_f32_16x16x32_bf16 v[30:33], v[30:33], v[38:41], 0
	s_waitcnt vmcnt(4)
	v_mfma_f32_16x16x32_bf16 v[30:33], v[240:243], v[68:71], v[30:33]
	s_waitcnt vmcnt(3)
	v_mfma_f32_16x16x32_bf16 v[34:37], v[34:37], v[38:41], 0
	s_waitcnt vmcnt(2)
	v_mfma_f32_16x16x32_bf16 v[34:37], v[244:247], v[68:71], v[34:37]
	s_waitcnt vmcnt(1)
	v_mfma_f32_16x16x32_bf16 v[38:41], v[58:61], v[38:41], 0
	s_waitcnt vmcnt(0)
; __device__ __forceinline__ f32x4 mfma16(bf16x8 a, bf16x8 b, f32x4 c) { return __builtin_amdgcn_mfma_f32_16x16x32_bf16(a, b, c, 0, 0, 0); }
; __device__ __forceinline__ bf16x8 pack8(f32x4 a, f32x4 b) { u32x4 w; w.x = pk2(a[0], a[1]); w.y = pk2(a[2], a[3]); w.z = pk2(b[0], b[1]); w.w = pk2(b[2], b[3]); return __builtin_bit_cast(bf16x8, w); }
; template <int BR>
; __device__ __forceinline__ void pattn_group(const bf16* P1, const bf16* VTB, LAS float* O, LAS float* Mx, LAS float* Ls, int t0, int h, int gi, int i16, int g) {
;     ...
;             acc = mfma16(ldfrag(krow), qf0, acc); acc = mfma16(ldfrag(krow + 32), qf1, acc);
;             s[kb][hf] = acc;
;         }
;     float mx = -1e30f;
; #pragma unroll
;     for (int kb = 0; kb < 5; ++kb)
; #pragma unroll
;         for (int hf = 0; hf < 2; ++hf)
; #pragma unroll
;             for (int e = 0; e < 4; ++e) {
;                 const int c = -144 + 32 * kb + 8 * g + 4 * hf + e, dist = i16 - c;
;                 const bool ok = dist >= 0 && dist <= 128 && (mq0 + c) >= 0;
;                 const float v = ok ? s[kb][hf][e] : -1e30f; s[kb][hf][e] = v; mx = fmaxf(mx, v);
;             }
;     mx = fmaxf(mx, __shfl_xor(mx, 16)); mx = fmaxf(mx, __shfl_xor(mx, 32));
;     float l = 0.f;
; #pragma unroll
;     for (int kb = 0; kb < 5; ++kb)
; #pragma unroll
;         for (int hf = 0; hf < 2; ++hf)
; #pragma unroll
;             for (int e = 0; e < 4; ++e) { const float v = s[kb][hf][e]; const float p = v > -1e29f ? __expf(v - mx) : 0.f; s[kb][hf][e] = p; l += p; }
;     l += __shfl_xor(l, 16); l += __shfl_xor(l, 32);
;     f32x4 ot[4];
; #pragma unroll
;     for (int dt = 0; dt < 4; ++dt) ot[dt] = (f32x4){0.f, 0.f, 0.f, 0.f};
; #pragma unroll
;     for (int kb = 0; kb < 5; ++kb) {
;         const bf16x8 pf = pack8(s[kb][0], s[kb][1]);
;         int m0 = mq0 - 144 + 32 * kb + 8 * g; m0 = m0 < 0 ? 0 : m0;
; #pragma unroll
;         for (int dt = 0; dt < 4; ++dt) {
;             const int f = h * 64 + 16 * dt + i16;
;             const bf16* vrow = BR == 0 ? VTB + (size_t)f * MT + m0 : (BR == 1 ? VTB + (size_t)f * 16384 + r * 4096 + m0 : VTB + (size_t)f * 16384 + r * 1024 + m0);
;             ot[dt] = mfma16(ldfrag(vrow), pf, ot[dt]);
	s_nop 1
	v_mfma_f32_16x16x32_bf16 v[38:41], v[248:251], v[68:71], v[38:41]
	v_readlane_b32 s98, v255, 36
	v_readlane_b32 s99, v255, 37
	v_lshlrev_b32_e32 v209, 15, v238
	v_add_u32_e32 v210, v116, v209
	v_add_u32_e32 v211, 0x80000, v210
	v_add_u32_e32 v224, 0x100000, v210
	v_add_u32_e32 v252, 0x180000, v210
	s_nop 0
	global_load_dwordx4 v[94:97], v210, s[98:99]
	global_load_dwordx4 v[98:101], v211, s[98:99]
	global_load_dwordx4 v[102:105], v224, s[98:99]
	global_load_dwordx4 v[106:109], v252, s[98:99]
	v_lshl_add_u32 v210, v52, 1, v209
	v_add_u32_e32 v210, 64, v210
	v_add_u32_e32 v211, 0x80000, v210
	v_add_u32_e32 v224, 0x100000, v210
	v_add_u32_e32 v252, 0x180000, v210
	global_load_dwordx4 v[110:113], v210, s[98:99]
	global_load_dwordx4 v[136:139], v211, s[98:99]
	global_load_dwordx4 v[140:143], v224, s[98:99]
	global_load_dwordx4 v[240:243], v252, s[98:99]
	v_lshl_add_u32 v210, v50, 1, v209
	v_add_u32_e32 v210, 0x80, v210
	v_add_u32_e32 v211, 0x80000, v210
	global_load_dwordx4 v[244:247], v210, s[98:99]
	global_load_dwordx4 v[248:251], v211, s[98:99]
	v_cndmask_b32_e64 v26, v226, v26, s[84:85]
	v_cndmask_b32_e64 v27, v226, v27, s[92:93]
	v_cndmask_b32_e64 v28, v226, v28, s[14:15]
	v_cndmask_b32_e64 v29, v226, v29, s[16:17]
	v_cndmask_b32_e64 v64, v226, v6, s[96:97]
	v_cndmask_b32_e64 v65, v226, v7, s[2:3]
	s_mov_b64 s[2:3], 0x80
	v_cndmask_b32_e64 v74, v226, v14, s[22:23]
	v_cndmask_b32_e64 v75, v226, v15, s[82:83]
	v_cndmask_b32_e64 v76, v226, v16, s[18:19]
	v_cndmask_b32_e64 v77, v226, v17, s[74:75]
	v_cndmask_b32_e64 v78, v226, v18, s[70:71]
	v_cndmask_b32_e64 v79, v226, v19, s[72:73]
	v_cndmask_b32_e64 v80, v226, v20, s[66:67]
	v_cndmask_b32_e64 v20, v226, v24, s[46:47]
	v_max3_f32 v57, v26, s65, v27
	v_max3_f32 v57, v57, v28, v29
	v_cndmask_b32_e64 v60, v226, v2, s[12:13]
	v_cndmask_b32_e64 v61, v226, v3, s[28:29]
	v_max3_f32 v2, v57, v60, v61
	v_cndmask_b32_e64 v62, v226, v4, s[30:31]
	v_cndmask_b32_e64 v63, v226, v5, s[10:11]
	v_max3_f32 v2, v2, v62, v63
	v_max3_f32 v2, v2, v64, v65
	v_cndmask_b32_e64 v66, v226, v8, s[6:7]
	v_cndmask_b32_e64 v67, v226, v9, s[8:9]
	v_max3_f32 v2, v2, v66, v67
	v_cndmask_b32_e64 v68, v226, v10, s[0:1]
	v_cndmask_b32_e64 v69, v226, v11, s[20:21]
	v_max3_f32 v2, v2, v68, v69
	v_cndmask_b32_e64 v70, v226, v12, s[24:25]
	v_cndmask_b32_e64 v71, v226, v13, s[26:27]
	v_max3_f32 v2, v2, v70, v71
	v_max3_f32 v2, v2, v74, v75
	v_max3_f32 v2, v2, v76, v77
	v_max3_f32 v2, v2, v78, v79
	v_cndmask_b32_e64 v59, v226, v21, s[68:69]
	v_max3_f32 v2, v2, v80, v59
	v_cndmask_b32_e64 v58, v226, v22, s[54:55]
	v_cndmask_b32_e64 v57, v226, v23, s[58:59]
	v_max3_f32 v2, v2, v58, v57
	v_cndmask_b32_e64 v18, v226, v25, s[52:53]
	v_readlane_b32 s0, v254, 41
	v_max3_f32 v2, v2, v20, v18
	v_cndmask_b32_e64 v16, v226, v30, s[94:95]
	v_cndmask_b32_e64 v15, v226, v31, s[38:39]
	v_readlane_b32 s1, v254, 42
	v_max3_f32 v2, v2, v16, v15
	v_cndmask_b32_e64 v12, v226, v33, s[62:63]
	v_cndmask_b32_e64 v13, v226, v32, s[0:1]
	v_max3_f32 v2, v2, v13, v12
	v_cndmask_b32_e64 v11, v226, v34, s[60:61]
	v_cndmask_b32_e64 v10, v226, v35, s[44:45]
	v_max3_f32 v2, v2, v11, v10
	v_cndmask_b32_e64 v9, v226, v36, s[36:37]
	v_cndmask_b32_e64 v7, v226, v37, s[40:41]
	v_max3_f32 v2, v2, v9, v7
	v_cndmask_b32_e64 v6, v226, v38, s[42:43]
	v_cndmask_b32_e64 v5, v226, v39, s[48:49]
	v_max3_f32 v4, v2, v6, v5
	v_cndmask_b32_e64 v3, v226, v40, s[50:51]
	v_cndmask_b32_e64 v2, v226, v41, s[56:57]
	v_max3_f32 v4, v4, v3, v2
	ds_bpermute_b32 v8, v129, v4
	v_cmp_lt_f32_e32 vcc, s78, v26
	v_readlane_b32 s0, v255, 36
	v_readlane_b32 s1, v255, 37
	v_readlane_b32 s34, v254, 37
	s_waitcnt lgkmcnt(0)
	v_max_f32_e32 v8, v8, v8
	v_max_f32_e32 v4, v4, v8
	ds_bpermute_b32 v8, v237, v4
	v_readlane_b32 s35, v254, 38
	s_waitcnt lgkmcnt(0)
	v_max_f32_e32 v8, v8, v8
	v_max_f32_e32 v34, v4, v8
	v_sub_f32_e32 v4, v26, v34
	v_mul_f32_e32 v4, 0x3fb8aa3b, v4
	v_sub_f32_e32 v8, v27, v34
	v_exp_f32_e32 v4, v4
	v_mul_f32_e32 v8, 0x3fb8aa3b, v8
	v_exp_f32_e32 v8, v8
	v_sub_f32_e32 v23, v62, v34
	v_cndmask_b32_e32 v4, 0, v4, vcc
	v_cmp_lt_f32_e32 vcc, s78, v27
	v_add_f32_e32 v14, 0, v4
	v_mul_f32_e32 v23, 0x3fb8aa3b, v23
	v_cndmask_b32_e32 v8, 0, v8, vcc
	v_add_f32_e32 v17, v8, v14
	v_sub_f32_e32 v14, v28, v34
	v_mul_f32_e32 v14, 0x3fb8aa3b, v14
	v_exp_f32_e32 v14, v14
	v_cmp_lt_f32_e32 vcc, s78, v28
	v_exp_f32_e32 v23, v23
	v_sub_f32_e32 v27, v68, v34
	v_cndmask_b32_e32 v14, 0, v14, vcc
	v_add_f32_e32 v19, v14, v17
	v_sub_f32_e32 v17, v29, v34
	v_mul_f32_e32 v17, 0x3fb8aa3b, v17
	v_exp_f32_e32 v17, v17
	v_cmp_lt_f32_e32 vcc, s78, v29
	v_mul_f32_e32 v27, 0x3fb8aa3b, v27
	v_exp_f32_e32 v27, v27
	v_cndmask_b32_e32 v17, 0, v17, vcc
	v_add_f32_e32 v21, v17, v19
	v_sub_f32_e32 v19, v60, v34
	v_mul_f32_e32 v19, 0x3fb8aa3b, v19
	v_exp_f32_e32 v19, v19
	v_cmp_lt_f32_e32 vcc, s78, v60
	v_sub_f32_e32 v31, v78, v34
	v_mul_f32_e32 v31, 0x3fb8aa3b, v31
	v_cndmask_b32_e32 v19, 0, v19, vcc
	v_add_f32_e32 v22, v19, v21
	v_sub_f32_e32 v21, v61, v34
	v_mul_f32_e32 v21, 0x3fb8aa3b, v21
	v_exp_f32_e32 v21, v21
	v_cmp_lt_f32_e32 vcc, s78, v61
	v_exp_f32_e32 v31, v31
	s_nop 0
	v_cndmask_b32_e32 v21, 0, v21, vcc
	v_cmp_lt_f32_e32 vcc, s78, v62
	v_add_f32_e32 v22, v21, v22
	s_nop 0
	v_cndmask_b32_e32 v72, 0, v23, vcc
	v_sub_f32_e32 v23, v63, v34
	v_mul_f32_e32 v23, 0x3fb8aa3b, v23
	v_exp_f32_e32 v23, v23
	v_cmp_lt_f32_e32 vcc, s78, v63
	v_add_f32_e32 v22, v72, v22
	s_nop 0
	v_cndmask_b32_e32 v73, 0, v23, vcc
	v_add_f32_e32 v23, v73, v22
	v_sub_f32_e32 v22, v64, v34
	v_mul_f32_e32 v22, 0x3fb8aa3b, v22
	v_exp_f32_e32 v22, v22
	v_cmp_lt_f32_e32 vcc, s78, v64
	s_nop 1
	v_cndmask_b32_e32 v22, 0, v22, vcc
; template <int BR>
; __device__ __forceinline__ void pattn_group(const bf16* P1, const bf16* VTB, LAS float* O, LAS float* Mx, LAS float* Ls, int t0, int h, int gi, int i16, int g) {
;     ...
;     float l = 0.f;
; #pragma unroll
;     for (int kb = 0; kb < 5; ++kb)
; #pragma unroll
;         for (int hf = 0; hf < 2; ++hf)
; #pragma unroll
;             for (int e = 0; e < 4; ++e) { const float v = s[kb][hf][e]; const float p = v > -1e29f ? __expf(v - mx) : 0.f; s[kb][hf][e] = p; l += p; }
;     l += __shfl_xor(l, 16); l += __shfl_xor(l, 32);
	v_add_f32_e32 v24, v22, v23
	v_sub_f32_e32 v23, v65, v34
	v_mul_f32_e32 v23, 0x3fb8aa3b, v23
	v_exp_f32_e32 v23, v23
	v_cmp_lt_f32_e32 vcc, s78, v65
	s_nop 1
	v_cndmask_b32_e32 v23, 0, v23, vcc
	v_add_f32_e32 v25, v23, v24
	v_sub_f32_e32 v24, v66, v34
	v_mul_f32_e32 v24, 0x3fb8aa3b, v24
	v_exp_f32_e32 v24, v24
	v_cmp_lt_f32_e32 vcc, s78, v66
	s_nop 1
	v_cndmask_b32_e32 v24, 0, v24, vcc
	v_add_f32_e32 v26, v24, v25
	v_sub_f32_e32 v25, v67, v34
	v_mul_f32_e32 v25, 0x3fb8aa3b, v25
	v_exp_f32_e32 v25, v25
	v_cmp_lt_f32_e32 vcc, s78, v67
	s_nop 1
	v_cndmask_b32_e32 v25, 0, v25, vcc
	v_cmp_lt_f32_e32 vcc, s78, v68
	v_add_f32_e32 v26, v25, v26
	s_nop 0
	v_cndmask_b32_e32 v68, 0, v27, vcc
	v_sub_f32_e32 v27, v69, v34
	v_mul_f32_e32 v27, 0x3fb8aa3b, v27
	v_exp_f32_e32 v27, v27
	v_cmp_lt_f32_e32 vcc, s78, v69
	v_add_f32_e32 v26, v68, v26
	s_nop 0
	v_cndmask_b32_e32 v69, 0, v27, vcc
	v_sub_f32_e32 v27, v70, v34
	v_mul_f32_e32 v27, 0x3fb8aa3b, v27
	v_exp_f32_e32 v27, v27
	v_cmp_lt_f32_e32 vcc, s78, v70
	v_add_f32_e32 v26, v69, v26
	s_nop 0
	v_cndmask_b32_e32 v70, 0, v27, vcc
	v_sub_f32_e32 v27, v71, v34
	v_mul_f32_e32 v27, 0x3fb8aa3b, v27
	v_exp_f32_e32 v27, v27
	v_cmp_lt_f32_e32 vcc, s78, v71
	v_add_f32_e32 v26, v70, v26
	s_nop 0
	v_cndmask_b32_e32 v71, 0, v27, vcc
	v_add_f32_e32 v27, v71, v26
	v_sub_f32_e32 v26, v74, v34
	v_mul_f32_e32 v26, 0x3fb8aa3b, v26
	v_exp_f32_e32 v26, v26
	v_cmp_lt_f32_e32 vcc, s78, v74
	s_nop 1
	v_cndmask_b32_e32 v26, 0, v26, vcc
	v_add_f32_e32 v28, v26, v27
	v_sub_f32_e32 v27, v75, v34
	v_mul_f32_e32 v27, 0x3fb8aa3b, v27
	v_exp_f32_e32 v27, v27
	v_cmp_lt_f32_e32 vcc, s78, v75
	s_nop 1
	v_cndmask_b32_e32 v27, 0, v27, vcc
	v_add_f32_e32 v29, v27, v28
	v_sub_f32_e32 v28, v76, v34
	v_mul_f32_e32 v28, 0x3fb8aa3b, v28
	v_exp_f32_e32 v28, v28
	v_cmp_lt_f32_e32 vcc, s78, v76
	s_nop 1
	v_cndmask_b32_e32 v28, 0, v28, vcc
	v_add_f32_e32 v30, v28, v29
	v_sub_f32_e32 v29, v77, v34
	v_mul_f32_e32 v29, 0x3fb8aa3b, v29
	v_exp_f32_e32 v29, v29
	v_cmp_lt_f32_e32 vcc, s78, v77
	s_nop 1
	v_cndmask_b32_e32 v29, 0, v29, vcc
	v_cmp_lt_f32_e32 vcc, s78, v78
	v_add_f32_e32 v30, v29, v30
	s_nop 0
	v_cndmask_b32_e32 v64, 0, v31, vcc
	v_sub_f32_e32 v31, v79, v34
	v_mul_f32_e32 v31, 0x3fb8aa3b, v31
	v_exp_f32_e32 v31, v31
	v_cmp_lt_f32_e32 vcc, s78, v79
	v_add_f32_e32 v30, v64, v30
	s_nop 0
	v_cndmask_b32_e32 v65, 0, v31, vcc
	v_sub_f32_e32 v31, v80, v34
	v_mul_f32_e32 v31, 0x3fb8aa3b, v31
	v_exp_f32_e32 v31, v31
	v_cmp_lt_f32_e32 vcc, s78, v80
	v_add_f32_e32 v30, v65, v30
	s_nop 0
	v_cndmask_b32_e32 v66, 0, v31, vcc
	v_sub_f32_e32 v31, v59, v34
	v_mul_f32_e32 v31, 0x3fb8aa3b, v31
	v_exp_f32_e32 v31, v31
	v_cmp_lt_f32_e32 vcc, s78, v59
	v_add_f32_e32 v30, v66, v30
	s_nop 0
	v_cndmask_b32_e32 v67, 0, v31, vcc
	v_add_f32_e32 v31, v67, v30
	v_sub_f32_e32 v30, v58, v34
	v_mul_f32_e32 v30, 0x3fb8aa3b, v30
	v_exp_f32_e32 v30, v30
	v_cmp_lt_f32_e32 vcc, s78, v58
	s_nop 1
	v_cndmask_b32_e32 v30, 0, v30, vcc
	v_add_f32_e32 v32, v30, v31
	v_sub_f32_e32 v31, v57, v34
	v_mul_f32_e32 v31, 0x3fb8aa3b, v31
	v_exp_f32_e32 v31, v31
	v_cmp_lt_f32_e32 vcc, s78, v57
	s_nop 1
	v_cndmask_b32_e32 v31, 0, v31, vcc
	v_cmp_lt_f32_e32 vcc, s78, v20
	v_sub_f32_e32 v20, v20, v34
	v_mul_f32_e32 v20, 0x3fb8aa3b, v20
	v_exp_f32_e32 v20, v20
	v_add_f32_e32 v33, v31, v32
	v_cndmask_b32_e32 v32, 0, v20, vcc
	v_cmp_lt_f32_e32 vcc, s78, v18
	v_sub_f32_e32 v18, v18, v34
	v_mul_f32_e32 v18, 0x3fb8aa3b, v18
	v_exp_f32_e32 v18, v18
	v_add_f32_e32 v20, v32, v33
	v_cndmask_b32_e32 v33, 0, v18, vcc
	v_cmp_lt_f32_e32 vcc, s78, v16
	v_sub_f32_e32 v16, v16, v34
	v_mul_f32_e32 v16, 0x3fb8aa3b, v16
	v_exp_f32_e32 v16, v16
	v_add_f32_e32 v18, v33, v20
	v_cndmask_b32_e32 v60, 0, v16, vcc
	v_cmp_lt_f32_e32 vcc, s78, v15
	v_sub_f32_e32 v15, v15, v34
	v_mul_f32_e32 v15, 0x3fb8aa3b, v15
	v_exp_f32_e32 v15, v15
	v_add_f32_e32 v16, v60, v18
	v_cndmask_b32_e32 v61, 0, v15, vcc
	v_cmp_lt_f32_e32 vcc, s78, v13
	v_sub_f32_e32 v13, v13, v34
	v_mul_f32_e32 v13, 0x3fb8aa3b, v13
	v_exp_f32_e32 v13, v13
	v_add_f32_e32 v15, v61, v16
	v_cndmask_b32_e32 v62, 0, v13, vcc
	v_cmp_lt_f32_e32 vcc, s78, v12
	v_sub_f32_e32 v12, v12, v34
	v_mul_f32_e32 v12, 0x3fb8aa3b, v12
	v_exp_f32_e32 v12, v12
	v_add_f32_e32 v13, v62, v15
	v_cndmask_b32_e32 v63, 0, v12, vcc
	v_cmp_lt_f32_e32 vcc, s78, v11
	v_sub_f32_e32 v11, v11, v34
	v_mul_f32_e32 v11, 0x3fb8aa3b, v11
	v_exp_f32_e32 v11, v11
	v_add_f32_e32 v12, v63, v13
	v_cndmask_b32_e32 v37, 0, v11, vcc
	v_cmp_lt_f32_e32 vcc, s78, v10
	v_sub_f32_e32 v10, v10, v34
	v_mul_f32_e32 v10, 0x3fb8aa3b, v10
	v_exp_f32_e32 v10, v10
	v_add_f32_e32 v11, v37, v12
	v_cndmask_b32_e32 v38, 0, v10, vcc
	v_cmp_lt_f32_e32 vcc, s78, v9
	v_sub_f32_e32 v9, v9, v34
	v_mul_f32_e32 v9, 0x3fb8aa3b, v9
	v_exp_f32_e32 v9, v9
	v_add_f32_e32 v10, v38, v11
	v_cndmask_b32_e32 v39, 0, v9, vcc
	v_cmp_lt_f32_e32 vcc, s78, v7
	v_sub_f32_e32 v7, v7, v34
	v_mul_f32_e32 v7, 0x3fb8aa3b, v7
	v_exp_f32_e32 v7, v7
	v_add_f32_e32 v9, v39, v10
	v_cndmask_b32_e32 v40, 0, v7, vcc
	v_cmp_lt_f32_e32 vcc, s78, v6
	v_sub_f32_e32 v6, v6, v34
	v_mul_f32_e32 v6, 0x3fb8aa3b, v6
	v_exp_f32_e32 v6, v6
	v_add_f32_e32 v7, v40, v9
	v_cndmask_b32_e32 v41, 0, v6, vcc
	v_cmp_lt_f32_e32 vcc, s78, v5
	v_sub_f32_e32 v5, v5, v34
	v_mul_f32_e32 v5, 0x3fb8aa3b, v5
	v_exp_f32_e32 v5, v5
	v_add_f32_e32 v6, v41, v7
	v_cndmask_b32_e32 v57, 0, v5, vcc
	v_cmp_lt_f32_e32 vcc, s78, v3
	v_sub_f32_e32 v3, v3, v34
	v_mul_f32_e32 v3, 0x3fb8aa3b, v3
	v_exp_f32_e32 v3, v3
	v_add_f32_e32 v5, v57, v6
	v_bfe_u32 v6, v73, 16, 1
	v_add3_u32 v6, v73, v6, s79
	v_cndmask_b32_e32 v58, 0, v3, vcc
	v_cmp_lt_f32_e32 vcc, s78, v2
	v_sub_f32_e32 v2, v2, v34
	v_mul_f32_e32 v2, 0x3fb8aa3b, v2
	v_exp_f32_e32 v2, v2
	v_add_f32_e32 v3, v58, v5
	v_bfe_u32 v5, v21, 16, 1
	v_add3_u32 v5, v21, v5, s79
	v_cndmask_b32_e32 v59, 0, v2, vcc
	v_add_f32_e32 v2, v59, v3
	ds_bpermute_b32 v3, v129, v2
	s_waitcnt lgkmcnt(0)
; __device__ __forceinline__ f32x4 mfma16(bf16x8 a, bf16x8 b, f32x4 c) { return __builtin_amdgcn_mfma_f32_16x16x32_bf16(a, b, c, 0, 0, 0); }
; __device__ __forceinline__ bf16x8 pack8(f32x4 a, f32x4 b) { u32x4 w; w.x = pk2(a[0], a[1]); w.y = pk2(a[2], a[3]); w.z = pk2(b[0], b[1]); w.w = pk2(b[2], b[3]); return __builtin_bit_cast(bf16x8, w); }
; template <int BR>
; __device__ __forceinline__ void pattn_group(const bf16* P1, const bf16* VTB, LAS float* O, LAS float* Mx, LAS float* Ls, int t0, int h, int gi, int i16, int g) {
;     ...
;     for (int kb = 0; kb < 5; ++kb) {
;         const bf16x8 pf = pack8(s[kb][0], s[kb][1]);
;         int m0 = mq0 - 144 + 32 * kb + 8 * g; m0 = m0 < 0 ? 0 : m0;
; #pragma unroll
;         for (int dt = 0; dt < 4; ++dt) {
;             const int f = h * 64 + 16 * dt + i16;
;             const bf16* vrow = BR == 0 ? VTB + (size_t)f * MT + m0 : (BR == 1 ? VTB + (size_t)f * 16384 + r * 4096 + m0 : VTB + (size_t)f * 16384 + r * 1024 + m0);
;             ot[dt] = mfma16(ldfrag(vrow), pf, ot[dt]);
;         }
;     }
	v_add_f32_e32 v35, v2, v3
	v_bfe_u32 v2, v4, 16, 1
	v_add3_u32 v2, v4, v2, s79
	v_bfe_u32 v3, v8, 16, 1
	v_lshrrev_b32_e32 v2, 16, v2
	v_add3_u32 v3, v8, v3, s79
	v_and_or_b32 v2, v3, s80, v2
	v_bfe_u32 v3, v14, 16, 1
	v_add3_u32 v3, v14, v3, s79
	v_bfe_u32 v4, v17, 16, 1
	v_lshrrev_b32_e32 v3, 16, v3
	v_add3_u32 v4, v17, v4, s79
	v_and_or_b32 v3, v4, s80, v3
	v_bfe_u32 v4, v19, 16, 1
	v_add3_u32 v4, v19, v4, s79
	v_lshrrev_b32_e32 v4, 16, v4
	v_and_or_b32 v4, v5, s80, v4
	v_bfe_u32 v5, v72, 16, 1
	v_add3_u32 v5, v72, v5, s79
	v_lshrrev_b32_e32 v5, 16, v5
	v_lshl_add_u64 v[72:73], s[0:1], 0, v[116:117]
	v_lshlrev_b32_e32 v116, 1, v56
	v_and_or_b32 v5, v6, s80, v5
	v_lshl_add_u64 v[6:7], v[72:73], 0, v[116:117]
	v_lshl_add_u64 v[14:15], v[72:73], 0, v[44:45]
	s_nop 0
	ds_bpermute_b32 v36, v237, v35
	s_nop 0
	s_nop 0
	s_waitcnt vmcnt(9)
	v_mfma_f32_16x16x32_bf16 v[10:13], v[94:97], v[2:5], 0
	v_lshl_add_u64 v[6:7], v[72:73], 0, v[54:55]
	s_nop 0
	s_nop 0
	s_waitcnt vmcnt(7)
	v_mfma_f32_16x16x32_bf16 v[18:21], v[102:105], v[2:5], 0
	v_lshl_add_u64 v[14:15], v[72:73], 0, v[42:43]
	s_nop 0
	s_nop 0
	s_waitcnt vmcnt(8)
	v_mfma_f32_16x16x32_bf16 v[6:9], v[98:101], v[2:5], 0
	s_nop 0
	s_waitcnt vmcnt(6)
	v_mfma_f32_16x16x32_bf16 v[14:17], v[106:109], v[2:5], 0
	v_lshl_add_u32 v210, v50, 1, v209
	v_add_u32_e32 v210, 0x80, v210
	v_add_u32_e32 v211, 0x100000, v210
	global_load_dwordx4 v[94:97], v211, s[98:99]
	v_add_u32_e32 v211, 0x180000, v210
	global_load_dwordx4 v[98:101], v211, s[98:99]
	v_lshl_add_u32 v210, v48, 1, v209
	v_add_u32_e32 v210, 0xc0, v210
	global_load_dwordx4 v[102:105], v210, s[98:99]
	v_add_u32_e32 v211, 0x80000, v210
	global_load_dwordx4 v[106:109], v211, s[98:99]
	v_bfe_u32 v2, v22, 16, 1
	v_add3_u32 v2, v22, v2, s79
	v_bfe_u32 v3, v23, 16, 1
	v_lshrrev_b32_e32 v2, 16, v2
	v_add3_u32 v3, v23, v3, s79
	v_and_or_b32 v22, v3, s80, v2
	v_bfe_u32 v2, v24, 16, 1
	v_add3_u32 v2, v24, v2, s79
	v_bfe_u32 v3, v25, 16, 1
	v_lshrrev_b32_e32 v2, 16, v2
	v_add3_u32 v3, v25, v3, s79
	v_and_or_b32 v23, v3, s80, v2
	v_bfe_u32 v2, v68, 16, 1
	v_add3_u32 v2, v68, v2, s79
	v_bfe_u32 v3, v69, 16, 1
	v_lshrrev_b32_e32 v2, 16, v2
	v_add3_u32 v3, v69, v3, s79
	v_and_or_b32 v24, v3, s80, v2
	v_bfe_u32 v2, v70, 16, 1
	v_add3_u32 v2, v70, v2, s79
	v_bfe_u32 v3, v71, 16, 1
	v_lshrrev_b32_e32 v2, 16, v2
	v_add3_u32 v3, v71, v3, s79
	v_and_or_b32 v25, v3, s80, v2
	v_lshl_add_u64 v[2:3], v[52:53], 1, s[0:1]
	v_lshl_add_u64 v[52:53], v[2:3], 0, 64
	v_lshl_add_u64 v[2:3], v[2:3], 0, v[116:117]
	s_nop 0
	s_nop 0
	s_waitcnt vmcnt(9)
	v_mfma_f32_16x16x32_bf16 v[10:13], v[110:113], v[22:25], v[10:13]
	v_lshl_add_u64 v[2:3], v[52:53], 0, v[54:55]
	s_nop 0
	s_nop 0
	s_waitcnt vmcnt(8)
	v_mfma_f32_16x16x32_bf16 v[2:5], v[136:139], v[22:25], v[6:9]
	s_nop 2
	v_lshl_add_u64 v[6:7], v[52:53], 0, v[44:45]
	s_nop 0
	s_nop 0
	s_waitcnt vmcnt(7)
	v_mfma_f32_16x16x32_bf16 v[6:9], v[140:143], v[22:25], v[18:21]
	s_nop 2
	v_lshl_add_u64 v[18:19], v[52:53], 0, v[42:43]
	s_nop 0
	s_nop 0
	s_waitcnt vmcnt(6)
	v_mfma_f32_16x16x32_bf16 v[14:17], v[240:243], v[22:25], v[14:17]
	v_lshl_add_u32 v210, v48, 1, v209
	v_add_u32_e32 v210, 0xc0, v210
	v_add_u32_e32 v211, 0x100000, v210
	global_load_dwordx4 v[110:113], v211, s[98:99]
	v_add_u32_e32 v211, 0x180000, v210
	global_load_dwordx4 v[136:139], v211, s[98:99]
	v_lshl_add_u32 v210, v46, 1, v209
	v_add_u32_e32 v210, 0x100, v210
	global_load_dwordx4 v[140:143], v210, s[98:99]
	v_add_u32_e32 v211, 0x80000, v210
	global_load_dwordx4 v[240:243], v211, s[98:99]
	v_bfe_u32 v18, v26, 16, 1
	v_add3_u32 v18, v26, v18, s79
	v_bfe_u32 v19, v27, 16, 1
	v_lshrrev_b32_e32 v18, 16, v18
	v_add3_u32 v19, v27, v19, s79
	v_and_or_b32 v18, v19, s80, v18
	v_bfe_u32 v19, v28, 16, 1
	v_add3_u32 v19, v28, v19, s79
	v_bfe_u32 v20, v29, 16, 1
	v_lshrrev_b32_e32 v19, 16, v19
	v_add3_u32 v20, v29, v20, s79
	v_and_or_b32 v19, v20, s80, v19
	v_bfe_u32 v20, v64, 16, 1
	v_add3_u32 v20, v64, v20, s79
	v_bfe_u32 v21, v65, 16, 1
	v_lshrrev_b32_e32 v20, 16, v20
	v_add3_u32 v21, v65, v21, s79
	v_and_or_b32 v20, v21, s80, v20
	v_bfe_u32 v21, v66, 16, 1
	v_add3_u32 v21, v66, v21, s79
	v_bfe_u32 v22, v67, 16, 1
	v_lshrrev_b32_e32 v21, 16, v21
	v_add3_u32 v22, v67, v22, s79
	v_and_or_b32 v21, v22, s80, v21
	v_lshl_add_u64 v[22:23], v[50:51], 1, s[0:1]
	v_lshl_add_u64 v[50:51], v[22:23], 0, s[2:3]
	v_lshl_add_u64 v[22:23], v[22:23], 0, v[116:117]
	s_nop 0
	s_mov_b64 s[2:3], 0xc0
	s_nop 0
	s_waitcnt vmcnt(9)
	v_mfma_f32_16x16x32_bf16 v[10:13], v[244:247], v[18:21], v[10:13]
	v_lshl_add_u64 v[22:23], v[50:51], 0, v[54:55]
	s_nop 0
	s_nop 0
	s_waitcnt vmcnt(8)
	v_mfma_f32_16x16x32_bf16 v[22:25], v[248:251], v[18:21], v[2:5]
	v_lshl_add_u32 v210, v46, 1, v209
	v_add_u32_e32 v210, 0x100, v210
	v_add_u32_e32 v211, 0x100000, v210
	global_load_dwordx4 v[244:247], v211, s[98:99]
	v_add_u32_e32 v211, 0x180000, v210
	global_load_dwordx4 v[248:251], v211, s[98:99]
	s_nop 2
	v_lshl_add_u64 v[2:3], v[50:51], 0, v[44:45]
	s_nop 0
	s_nop 0
	s_waitcnt vmcnt(9)
; #define LAS __attribute__((address_space(3)))
; __device__ __forceinline__ f32x4 mfma16(bf16x8 a, bf16x8 b, f32x4 c) { return __builtin_amdgcn_mfma_f32_16x16x32_bf16(a, b, c, 0, 0, 0); }
; __device__ __forceinline__ bf16x8 pack8(f32x4 a, f32x4 b) { u32x4 w; w.x = pk2(a[0], a[1]); w.y = pk2(a[2], a[3]); w.z = pk2(b[0], b[1]); w.w = pk2(b[2], b[3]); return __builtin_bit_cast(bf16x8, w); }
; template <int BR>
; __device__ __forceinline__ void pattn_group(const bf16* P1, const bf16* VTB, LAS float* O, LAS float* Mx, LAS float* Ls, int t0, int h, int gi, int i16, int g) {
;     ...
;     for (int kb = 0; kb < 5; ++kb) {
;         const bf16x8 pf = pack8(s[kb][0], s[kb][1]);
;         int m0 = mq0 - 144 + 32 * kb + 8 * g; m0 = m0 < 0 ? 0 : m0;
; #pragma unroll
;         for (int dt = 0; dt < 4; ++dt) {
;             const int f = h * 64 + 16 * dt + i16;
;             const bf16* vrow = BR == 0 ? VTB + (size_t)f * MT + m0 : (BR == 1 ? VTB + (size_t)f * 16384 + r * 4096 + m0 : VTB + (size_t)f * 16384 + r * 1024 + m0);
;             ot[dt] = mfma16(ldfrag(vrow), pf, ot[dt]);
;         }
;     }
;     const int ql = ql0 + dil * i16;
;     LAS float* orow = O + ql * 68 + 4 * g;
;     if (BR == 0) {
; #pragma unroll
;         for (int dt = 0; dt < 4; ++dt) *(LAS f32x4*)(orow + 16 * dt) = ot[dt];
;         if (g == 0) { Mx[ql] = mx; Ls[ql] = l; }
;     } else {
;         const float Mo = Mx[ql], Lo = Ls[ql], Mn = fmaxf(Mo, mx), fo = __expf(Mo - Mn), fn = __expf(mx - Mn);
; #pragma unroll
;         for (int dt = 0; dt < 4; ++dt) { const f32x4 v = *(const LAS f32x4*)(orow + 16 * dt); *(LAS f32x4*)(orow + 16 * dt) = v * fo + ot[dt] * fn; }
;         if (g == 0) { Mx[ql] = Mn; Ls[ql] = Lo * fo + l * fn; }
	v_mfma_f32_16x16x32_bf16 v[26:29], v[94:97], v[18:21], v[6:9]
	v_lshl_add_u64 v[2:3], v[50:51], 0, v[42:43]
	s_nop 0
	s_nop 0
	s_waitcnt vmcnt(8)
	v_mfma_f32_16x16x32_bf16 v[14:17], v[98:101], v[18:21], v[14:17]
	v_bfe_u32 v2, v30, 16, 1
	v_add3_u32 v2, v30, v2, s79
	v_bfe_u32 v3, v31, 16, 1
	v_lshrrev_b32_e32 v2, 16, v2
	v_add3_u32 v3, v31, v3, s79
	v_and_or_b32 v30, v3, s80, v2
	v_bfe_u32 v2, v32, 16, 1
	v_add3_u32 v2, v32, v2, s79
	v_bfe_u32 v3, v33, 16, 1
	v_lshrrev_b32_e32 v2, 16, v2
	v_add3_u32 v3, v33, v3, s79
	v_and_or_b32 v31, v3, s80, v2
	v_bfe_u32 v2, v60, 16, 1
	v_add3_u32 v2, v60, v2, s79
	v_bfe_u32 v3, v61, 16, 1
	v_lshrrev_b32_e32 v2, 16, v2
	v_add3_u32 v3, v61, v3, s79
	v_and_or_b32 v32, v3, s80, v2
	v_bfe_u32 v2, v62, 16, 1
	v_add3_u32 v2, v62, v2, s79
	v_bfe_u32 v3, v63, 16, 1
	v_lshrrev_b32_e32 v2, 16, v2
	v_add3_u32 v3, v63, v3, s79
	v_and_or_b32 v33, v3, s80, v2
	v_lshl_add_u64 v[2:3], v[48:49], 1, s[0:1]
	v_lshl_add_u64 v[48:49], v[2:3], 0, s[2:3]
	v_lshl_add_u64 v[2:3], v[2:3], 0, v[116:117]
	s_nop 0
	v_lshl_add_u64 v[6:7], v[48:49], 0, v[54:55]
	s_nop 0
	s_nop 0
	s_waitcnt vmcnt(7)
	v_mfma_f32_16x16x32_bf16 v[2:5], v[102:105], v[30:33], v[10:13]
	s_nop 2
	v_lshl_add_u64 v[10:11], v[48:49], 0, v[44:45]
	s_nop 0
	s_nop 0
	s_waitcnt vmcnt(5)
	v_mfma_f32_16x16x32_bf16 v[18:21], v[110:113], v[30:33], v[26:29]
	v_lshl_add_u64 v[10:11], v[48:49], 0, v[42:43]
	s_nop 0
	s_waitcnt vmcnt(6)
	v_mfma_f32_16x16x32_bf16 v[6:9], v[106:109], v[30:33], v[22:25]
	s_nop 0
	s_waitcnt vmcnt(4)
	v_mfma_f32_16x16x32_bf16 v[22:25], v[136:139], v[30:33], v[14:17]
	v_bfe_u32 v10, v37, 16, 1
	v_add3_u32 v10, v37, v10, s79
	v_bfe_u32 v11, v38, 16, 1
	v_lshrrev_b32_e32 v10, 16, v10
	v_add3_u32 v11, v38, v11, s79
	v_and_or_b32 v26, v11, s80, v10
	v_bfe_u32 v10, v39, 16, 1
	v_add3_u32 v10, v39, v10, s79
	v_bfe_u32 v11, v40, 16, 1
	v_lshrrev_b32_e32 v10, 16, v10
	v_add3_u32 v11, v40, v11, s79
	v_and_or_b32 v27, v11, s80, v10
	v_bfe_u32 v10, v41, 16, 1
	v_add3_u32 v10, v41, v10, s79
	v_bfe_u32 v11, v57, 16, 1
	v_lshrrev_b32_e32 v10, 16, v10
	v_add3_u32 v11, v57, v11, s79
	v_and_or_b32 v28, v11, s80, v10
	v_bfe_u32 v10, v58, 16, 1
	v_add3_u32 v10, v58, v10, s79
	v_bfe_u32 v11, v59, 16, 1
	v_lshrrev_b32_e32 v10, 16, v10
	v_add3_u32 v11, v59, v11, s79
	v_and_or_b32 v29, v11, s80, v10
	v_lshl_add_u64 v[10:11], v[46:47], 1, s[0:1]
	s_mov_b64 s[0:1], 0x100
	v_lshl_add_u64 v[30:31], v[10:11], 0, s[0:1]
	v_lshl_add_u64 v[10:11], v[10:11], 0, v[116:117]
	s_nop 0
	s_nop 0
	s_waitcnt vmcnt(3)
	v_mfma_f32_16x16x32_bf16 v[14:17], v[140:143], v[26:29], v[2:5]
	s_nop 2
	v_lshl_add_u64 v[2:3], v[30:31], 0, v[54:55]
	s_nop 0
	s_nop 0
	s_waitcnt vmcnt(2)
	v_mfma_f32_16x16x32_bf16 v[10:13], v[240:243], v[26:29], v[6:9]
	v_lshl_add_u64 v[2:3], v[30:31], 0, v[44:45]
	s_nop 0
	s_nop 0
	s_waitcnt vmcnt(1)
	v_mfma_f32_16x16x32_bf16 v[6:9], v[244:247], v[26:29], v[18:21]
	v_lshl_add_u64 v[2:3], v[30:31], 0, v[42:43]
	s_nop 0
	s_nop 0
	ds_read_b32 v18, v218
	ds_read_b32 v19, v219
	s_nop 0
	s_waitcnt vmcnt(0)
	v_mfma_f32_16x16x32_bf16 v[2:5], v[248:251], v[26:29], v[22:25]
	s_waitcnt lgkmcnt(1)
	v_max_f32_e32 v20, v18, v18
	v_max_f32_e32 v21, v20, v34
	v_sub_f32_e32 v20, v34, v21
	v_sub_f32_e32 v18, v18, v21
	v_mul_f32_e32 v20, 0x3fb8aa3b, v20
	v_mul_f32_e32 v18, 0x3fb8aa3b, v18
	v_exp_f32_e32 v20, v20
	ds_read_b128 v[22:25], v223
	v_exp_f32_e32 v18, v18
	v_pk_mul_f32 v[16:17], v[16:17], v[20:21] op_sel_hi:[1,0]
	v_pk_mul_f32 v[14:15], v[14:15], v[20:21] op_sel_hi:[1,0]
	s_waitcnt lgkmcnt(0)
	v_pk_fma_f32 v[16:17], v[24:25], v[18:19], v[16:17] op_sel_hi:[1,0,1]
	v_pk_fma_f32 v[14:15], v[22:23], v[18:19], v[14:15] op_sel_hi:[1,0,1]
	ds_write_b128 v223, v[14:17]
	ds_read_b128 v[14:17], v223 offset:64
	v_pk_mul_f32 v[12:13], v[12:13], v[20:21] op_sel_hi:[1,0]
	v_pk_mul_f32 v[10:11], v[10:11], v[20:21] op_sel_hi:[1,0]
	v_pk_mul_f32 v[8:9], v[8:9], v[20:21] op_sel_hi:[1,0]
	v_pk_mul_f32 v[6:7], v[6:7], v[20:21] op_sel_hi:[1,0]
	s_waitcnt lgkmcnt(0)
	v_pk_fma_f32 v[12:13], v[16:17], v[18:19], v[12:13] op_sel_hi:[1,0,1]
	v_pk_fma_f32 v[10:11], v[14:15], v[18:19], v[10:11] op_sel_hi:[1,0,1]
	ds_write_b128 v223, v[10:13] offset:64
	ds_read_b128 v[10:13], v223 offset:128
	s_waitcnt lgkmcnt(0)
	v_pk_fma_f32 v[8:9], v[18:19], v[12:13], v[8:9] op_sel_hi:[0,1,1]
	v_pk_fma_f32 v[6:7], v[18:19], v[10:11], v[6:7] op_sel_hi:[0,1,1]
	ds_write_b128 v223, v[6:9] offset:128
	ds_read_b128 v[6:9], v223 offset:192
	s_waitcnt lgkmcnt(0)
	v_pk_mul_f32 v[6:7], v[18:19], v[6:7] op_sel_hi:[0,1]
	v_pk_mul_f32 v[8:9], v[18:19], v[8:9] op_sel_hi:[0,1]
	v_pk_fma_f32 v[4:5], v[4:5], v[20:21], v[8:9] op_sel_hi:[1,0,1]
	v_pk_fma_f32 v[2:3], v[2:3], v[20:21], v[6:7] op_sel_hi:[1,0,1]
	ds_write_b128 v223, v[2:5] offset:192
	s_and_saveexec_b64 s[0:1], s[34:35]
	s_cbranch_execz .LBB0_986
	v_add_f32_e32 v2, v35, v36
	v_mul_f32_e32 v2, v20, v2
	v_fmac_f32_e32 v2, v19, v18
	ds_write_b32 v218, v21
	ds_write_b32 v219, v2

; __global__ void __launch_bounds__(NTHREADS, 2) hymba_fwd(Args args) {
	.amdhsa_kernel _Z9hymba_fwd4Args
		.amdhsa_group_segment_fixed_size 0
		.amdhsa_private_segment_fixed_size 0
		.amdhsa_kernarg_size 464
		.amdhsa_user_sgpr_count 2
		.amdhsa_user_sgpr_dispatch_ptr 0
		.amdhsa_user_sgpr_queue_ptr 0
		.amdhsa_user_sgpr_kernarg_segment_ptr 1
		.amdhsa_user_sgpr_dispatch_id 0
		.amdhsa_user_sgpr_kernarg_preload_length 0
		.amdhsa_user_sgpr_kernarg_preload_offset 0
		.amdhsa_user_sgpr_private_segment_size 0
		.amdhsa_uses_dynamic_stack 0
		.amdhsa_enable_private_segment 0
		.amdhsa_system_sgpr_workgroup_id_x 1
		.amdhsa_system_sgpr_workgroup_id_y 0
		.amdhsa_system_sgpr_workgroup_id_z 0
		.amdhsa_system_sgpr_workgroup_info 0
		.amdhsa_system_vgpr_workitem_id 0
		.amdhsa_next_free_vgpr 256
		.amdhsa_next_free_sgpr 102
		.amdhsa_accum_offset 256
		.amdhsa_reserve_vcc 1
		.amdhsa_float_round_mode_32 0
		.amdhsa_float_round_mode_16_64 0
		.amdhsa_float_denorm_mode_32 3
		.amdhsa_float_denorm_mode_16_64 3
		.amdhsa_dx10_clamp 1
		.amdhsa_ieee_mode 1
		.amdhsa_fp16_overflow 0
		.amdhsa_tg_split 0
		.amdhsa_exception_fp_ieee_invalid_op 0
		.amdhsa_exception_fp_denorm_src 0
		.amdhsa_exception_fp_ieee_div_zero 0
		.amdhsa_exception_fp_ieee_overflow 0
		.amdhsa_exception_fp_ieee_underflow 0
		.amdhsa_exception_fp_ieee_inexact 0
		.amdhsa_exception_int_div_zero 0
	.end_amdhsa_kernel

; __global__ void __launch_bounds__(NTHREADS, 2) hymba_fwd(Args args) {
amdhsa.kernels:
  - .agpr_count:     0
    .args:
      - .offset:         0
        .size:           208
        .value_kind:     by_value
      - .offset:         208
        .size:           4
        .value_kind:     hidden_block_count_x
      - .offset:         212
        .size:           4
        .value_kind:     hidden_block_count_y
      - .offset:         216
        .size:           4
        .value_kind:     hidden_block_count_z
      - .offset:         220
        .size:           2
        .value_kind:     hidden_group_size_x
      - .offset:         222
        .size:           2
        .value_kind:     hidden_group_size_y
      - .offset:         224
        .size:           2
        .value_kind:     hidden_group_size_z
      - .offset:         226
        .size:           2
        .value_kind:     hidden_remainder_x
      - .offset:         228
        .size:           2
        .value_kind:     hidden_remainder_y
      - .offset:         230
        .size:           2
        .value_kind:     hidden_remainder_z
      - .offset:         248
        .size:           8
        .value_kind:     hidden_global_offset_x
      - .offset:         256
        .size:           8
        .value_kind:     hidden_global_offset_y
      - .offset:         264
        .size:           8
        .value_kind:     hidden_global_offset_z
      - .offset:         272
        .size:           2
        .value_kind:     hidden_grid_dims
      - .offset:         328
        .size:           4
        .value_kind:     hidden_dynamic_lds_size
    .group_segment_fixed_size: 0
    .kernarg_segment_align: 8
    .kernarg_segment_size: 464
    .language:       OpenCL C
    .language_version:
      - 2
      - 0
    .max_flat_workgroup_size: 512
    .name:           _Z9hymba_fwd4Args
    .private_segment_fixed_size: 0
    .sgpr_count:     108
    .sgpr_spill_count: 252
    .symbol:         _Z9hymba_fwd4Args.kd
    .uniform_work_group_size: 1
    .uses_dynamic_stack: false
    .vgpr_count:     256
    .vgpr_spill_count: 0
    .wavefront_size: 64
